# E_IN pair tiles: every WG's first unit is a 128x256 pair, then 40 singles per XCD
# speedup vs baseline: 1.0164x; 1.0090x over previous
.Ltr414:
	s_branch .LBB0_414

.LBB0_277:
	s_andn2_b64 vcc, exec, s[0:1]
	s_cbranch_vccnz .LBB0_354
	s_cmp_lg_u32 s27, 1
	s_mov_b64 s[0:1], -1
	s_cbranch_scc0 .LBB0_310
	s_load_dword s0, s[96:97], 0x0
	s_and_b32 s20, s74, 7
	s_waitcnt lgkmcnt(0)
	s_lshr_b32 s13, s0, 6
	v_cvt_f32_u32_e32 v0, s13
	s_sub_i32 s1, 0, s13
	s_add_i32 s0, s13, 27
	v_rcp_iflag_f32_e32 v0, v0
	s_nop 0
	v_mul_f32_e32 v0, 0x4f7ffffe, v0
	v_cvt_u32_f32_e32 v0, v0
	s_nop 0
	v_readfirstlane_b32 s8, v0
	s_mul_i32 s1, s1, s8
	s_mul_hi_u32 s1, s8, s1
	s_add_i32 s8, s8, s1
	s_mul_hi_u32 s1, s0, s8
	s_mul_i32 s8, s1, s13
	s_sub_i32 s0, s0, s8
	s_add_i32 s9, s1, 1
	s_sub_i32 s8, s0, s13
	s_cmp_ge_u32 s0, s13
	s_cselect_b32 s1, s9, s1
	s_cselect_b32 s0, s8, s0
	s_add_i32 s8, s1, 1
	s_cmp_ge_u32 s0, s13
	s_cselect_b32 s21, s8, s1
	s_mul_i32 s21, s21, 6
	s_cmp_ge_u32 s20, s21
	s_cbranch_scc1 .LBB0_309
	s_mov_b32 s63, 1
	s_mov_b32 s62, 0
	s_cmp_eq_u32 s13, 8
	s_cbranch_scc0 .Lin_orig1
	s_mov_b32 s63, 0
	s_lshr_b32 s20, s74, 3
	s_movk_i32 s21, 0x68
	s_cmp_lt_u32 s20, 64
	s_cbranch_scc0 .Lid_s1
	s_mul_hi_u32 s8, s20, 0x2aaaaaab
	s_mul_i32 s9, s8, 6
	s_sub_i32 s9, s20, s9
	s_lshl_b32 s8, s8, 1
	s_branch .Lid_e1
.Lid_s1:
	s_add_i32 s9, s20, 0xffffffc0
	s_cmp_lt_u32 s9, 4
	s_cbranch_scc0 .Lid_t1
	s_and_b32 s8, s9, 1
	s_add_i32 s8, s8, 20
	s_lshr_b32 s9, s9, 1
	s_add_i32 s9, s9, 4
	s_branch .Lid_e1
.Lid_t1:
	s_add_i32 s9, s9, -4
	s_mul_hi_u32 s8, s9, 0x2aaaaaab
	s_mul_i32 s11, s8, 6
	s_sub_i32 s9, s9, s11
	s_add_i32 s8, s8, 22
.Lid_e1:
	s_lshl_b32 s10, s9, 3
	s_and_b32 s9, s74, 7
	s_or_b32 s10, s10, s9
	s_lshl_b32 s10, s10, 7
	s_lshl_b32 s8, s8, 7
	s_add_i32 s20, s20, 64
	s_mov_b64 s[0:1], -1
	s_branch .LBB0_286

.LBB0_288:
	s_or_b64 exec, exec, s[10:11]
	v_lshl_add_u64 v[0:1], s[8:9], 0, v[84:85]
	s_waitcnt lgkmcnt(0)
	s_barrier
	v_lshl_add_u64 v[4:5], v[70:71], 1, v[0:1]
	ds_read_b128 v[0:3], v107 offset:49152
	s_mov_b64 s[16:17], -1
	s_and_b64 vcc, exec, s[0:1]
	s_mov_b32 s10, s48
	s_waitcnt lgkmcnt(0)
	global_store_dwordx4 v[4:5], v[0:3], off
	s_nop 1
	v_lshl_add_u64 v[0:1], s[8:9], 0, v[86:87]
	v_lshl_add_u64 v[4:5], v[74:75], 1, v[0:1]
	ds_read_b128 v[0:3], v108 offset:49152
	s_waitcnt lgkmcnt(0)
	global_store_dwordx4 v[4:5], v[0:3], off
	s_nop 1
	v_lshl_add_u64 v[0:1], s[8:9], 0, v[88:89]
	v_lshl_add_u64 v[4:5], v[78:79], 1, v[0:1]
	ds_read_b128 v[0:3], v109 offset:49152
	s_waitcnt lgkmcnt(0)
	global_store_dwordx4 v[4:5], v[0:3], off
	s_nop 1
	v_lshl_add_u64 v[0:1], s[8:9], 0, v[90:91]
	v_lshl_add_u64 v[4:5], v[82:83], 1, v[0:1]
	ds_read_b128 v[0:3], v110 offset:49152
	s_mov_b32 s8, s43
	s_waitcnt lgkmcnt(0)
	global_store_dwordx4 v[4:5], v[0:3], off
	s_waitcnt lgkmcnt(0)
	s_barrier
	s_cmp_eq_u32 s62, 2
	s_cbranch_scc0 .Lin_eout
	s_mov_b32 s62, 0
	s_mov_b32 s48, s60
	s_mov_b32 s43, s61
	s_mov_b32 s9, 0
	v_mov_b32_e32 v32, v170
	v_mov_b32_e32 v33, v171
	v_mov_b32_e32 v34, v172
	v_mov_b32_e32 v35, v173
	v_mov_b32_e32 v36, v174
	v_mov_b32_e32 v37, v175
	v_mov_b32_e32 v38, v176
	v_mov_b32_e32 v39, v177
	v_mov_b32_e32 v40, v178
	v_mov_b32_e32 v41, v179
	v_mov_b32_e32 v42, v180
	v_mov_b32_e32 v43, v181
	v_mov_b32_e32 v44, v182
	v_mov_b32_e32 v45, v183
	v_mov_b32_e32 v46, v184
	v_mov_b32_e32 v47, v185
	v_mov_b32_e32 v48, v186
	v_mov_b32_e32 v49, v187
	v_mov_b32_e32 v50, v188
	v_mov_b32_e32 v51, v189
	v_mov_b32_e32 v52, v190
	v_mov_b32_e32 v53, v191
	v_mov_b32_e32 v54, v192
	v_mov_b32_e32 v55, v193
	v_mov_b32_e32 v56, v194
	v_mov_b32_e32 v57, v195
	v_mov_b32_e32 v58, v196
	v_mov_b32_e32 v59, v197
	v_mov_b32_e32 v60, v198
	v_mov_b32_e32 v61, v199
	v_mov_b32_e32 v62, v200
	v_mov_b32_e32 v63, v201
	v_mov_b32_e32 v16, v202
	v_mov_b32_e32 v17, v203
	v_mov_b32_e32 v18, v204
	v_mov_b32_e32 v19, v205
	v_mov_b32_e32 v20, v206
	v_mov_b32_e32 v21, v207
	v_mov_b32_e32 v22, v208
	v_mov_b32_e32 v23, v209
	v_mov_b32_e32 v24, v210
	v_mov_b32_e32 v25, v211
	v_mov_b32_e32 v26, v212
	v_mov_b32_e32 v27, v213
	v_mov_b32_e32 v28, v214
	v_mov_b32_e32 v29, v215
	v_mov_b32_e32 v30, v216
	v_mov_b32_e32 v31, v217
	v_mov_b32_e32 v0, v226
	v_mov_b32_e32 v1, v227
	v_mov_b32_e32 v2, v228
	v_mov_b32_e32 v3, v229
	v_mov_b32_e32 v4, v230
	v_mov_b32_e32 v5, v231
	v_mov_b32_e32 v6, v232
	v_mov_b32_e32 v7, v233
	v_mov_b32_e32 v8, v234
	v_mov_b32_e32 v9, v235
	v_mov_b32_e32 v10, v236
	v_mov_b32_e32 v11, v237
	v_mov_b32_e32 v12, v238
	v_mov_b32_e32 v13, v239
	v_mov_b32_e32 v14, v240
	v_mov_b32_e32 v15, v241
	v_mov_b32_e32 v112, v243
	v_mov_b32_e32 v95, v248
	v_mov_b32_e32 v212, 0x358637bd
	v_mbcnt_lo_u32_b32 v213, -1, 0
	v_mbcnt_hi_u32_b32 v213, -1, v213
	s_branch .LBB0_300
.Lin_eout:
	s_cbranch_vccnz .LBB0_309
.LBB0_289:
	s_mov_b64 s[14:15], 0
	s_cmp_ge_i32 s20, s21
	s_cbranch_scc0 .LBB0_305

.LBB0_292:
	s_or_b64 exec, exec, s[18:19]
	s_add_i32 s9, s10, 0xfffff000
	s_lshr_b32 s9, s9, 10
	s_add_i32 s9, s9, 1
	s_cmpk_gt_i32 s10, 0xfff
	s_cselect_b32 s9, s9, 0
	s_mul_i32 s11, s12, 3
	s_add_i32 s9, s9, s11
	s_mul_hi_u32 s11, s9, 0xd000
	s_mul_i32 s9, s9, 0xd000
	s_add_u32 s49, s30, s9
	s_addc_u32 s11, s34, s11
	s_ashr_i32 s9, s8, 31
	s_lshl_b64 s[18:19], s[8:9], 2
	s_add_u32 s18, s49, s18
	s_addc_u32 s19, s11, s19
	v_lshl_add_u64 v[0:1], s[18:19], 0, v[116:117]
	v_mov_b32_e32 v95, v117
	v_lshl_add_u64 v[0:1], v[0:1], 0, v[94:95]
	global_load_dword v112, v[0:1], off
	global_load_dword v95, v[0:1], off offset:128
	global_load_dword v243, v[0:1], off offset:512
	global_load_dword v248, v[0:1], off offset:640
	s_ashr_i32 s18, s10, 7
	s_ashr_i32 s19, s18, 31
	s_lshl_b64 s[18:19], s[18:19], 18
	v_lshl_add_u64 v[96:97], v[64:65], 0, s[18:19]
	s_ashr_i32 s18, s8, 7
	s_ashr_i32 s19, s18, 31
	s_lshl_b64 s[18:19], s[18:19], 18
	v_lshl_add_u64 v[98:99], v[66:67], 0, s[18:19]
	s_mov_b64 s[18:19], -1
	s_andn2_b64 vcc, exec, s[16:17]
	v_add_u32_e32 v132, 0x400, v100
	v_add_u32_e32 v131, 0x2000, v100
	v_add_u32_e32 v130, 0x2400, v100
	v_add_u32_e32 v129, 0x4000, v100
	v_add_u32_e32 v128, 0x4400, v100
	v_add_u32_e32 v125, 0x6000, v100
	v_add_u32_e32 v122, 0x6400, v100
	v_add_u32_e32 v119, 0x8000, v100
	v_add_u32_e32 v115, 0x8400, v100
	v_add_u32_e32 v114, 0xa000, v100
	v_add_u32_e32 v113, 0xa400, v100
	s_cbranch_vccnz .LBB0_294
	v_readfirstlane_b32 s11, v100
	s_mov_b32 m0, s11
	s_mov_b64 s[16:17], 0x400
	v_readfirstlane_b32 s11, v132
	global_load_lds_dwordx4 v[96:97], off
	v_lshl_add_u64 v[0:1], v[96:97], 0, s[16:17]
	s_mov_b32 m0, s11
	v_readfirstlane_b32 s11, v131
	global_load_lds_dwordx4 v[0:1], off
	s_mov_b32 m0, s11
	v_readfirstlane_b32 s11, v130
	global_load_lds_dwordx4 v[98:99], off
	v_lshl_add_u64 v[0:1], v[98:99], 0, s[16:17]
	s_mov_b32 m0, s11
	v_readfirstlane_b32 s11, v129
	global_load_lds_dwordx4 v[0:1], off
	v_lshl_add_u64 v[0:1], v[96:97], 0, s[44:45]
	s_mov_b32 m0, s11
	v_readfirstlane_b32 s11, v128
	global_load_lds_dwordx4 v[0:1], off
	v_lshl_add_u64 v[0:1], v[96:97], 0, s[66:67]
	s_mov_b32 m0, s11
	v_readfirstlane_b32 s11, v125
	global_load_lds_dwordx4 v[0:1], off
	v_lshl_add_u64 v[0:1], v[98:99], 0, s[44:45]
	s_mov_b32 m0, s11
	v_readfirstlane_b32 s11, v122
	global_load_lds_dwordx4 v[0:1], off
	v_lshl_add_u64 v[0:1], v[98:99], 0, s[66:67]
	s_mov_b32 m0, s11
	v_readfirstlane_b32 s11, v119
	global_load_lds_dwordx4 v[0:1], off
	v_lshl_add_u64 v[0:1], v[96:97], 0, s[28:29]
	s_mov_b32 m0, s11
	s_mov_b64 s[16:17], 0x4400
	v_readfirstlane_b32 s11, v115
	global_load_lds_dwordx4 v[0:1], off
	v_lshl_add_u64 v[0:1], v[96:97], 0, s[16:17]
	s_mov_b32 m0, s11
	v_readfirstlane_b32 s11, v114
	global_load_lds_dwordx4 v[0:1], off
	v_lshl_add_u64 v[0:1], v[98:99], 0, s[28:29]
	s_mov_b32 m0, s11
	v_readfirstlane_b32 s11, v113
	global_load_lds_dwordx4 v[0:1], off
	v_lshl_add_u64 v[0:1], v[98:99], 0, s[16:17]
	s_mov_b32 m0, s11
	s_mov_b64 s[18:19], 0
	global_load_lds_dwordx4 v[0:1], off
	s_waitcnt vmcnt(8)

.LBB0_296:
	s_cmp_eq_u32 s63, 0
	s_cbranch_scc1 .Lin_pair
	s_mov_b32 s62, 0
	s_branch .Lin_single
.Lin_pair:
	s_mov_b32 s63, 1
	s_mov_b32 s62, 1
	v_add_u32_e32 v113, v101, v103
	v_add_u32_e32 v119, v102, v103
	v_add_u32_e32 v122, v101, v104
	v_add_u32_e32 v125, v102, v104
	v_add_u32_e32 v132, 0x4000, v119
	v_add_u32_e32 v133, 0x4000, v125
	v_readfirstlane_b32 s50, v100
	s_mov_b64 s[72:73], 0x40000
	s_mov_b64 s[86:87], 0x4000
	s_add_u32 s51, s50, 0x4000
	s_add_u32 s52, s50, 0x8000
	s_add_u32 s53, s50, 0x2000
	s_add_u32 s54, s50, 0x6000
	s_add_u32 s55, s50, 0xa000
	s_add_u32 s56, s50, 0xc000
	s_add_u32 s57, s50, 0xe000
	s_add_u32 s58, s50, 0x12000
	v_lshl_add_u64 v[114:115], v[98:99], 0, s[72:73]
	s_mov_b32 m0, s56
	s_nop 0
	global_load_lds_dwordx4 v[114:115], off
	global_load_lds_dwordx4 v[114:115], off offset:1024
	v_lshl_add_u64 v[114:115], v[114:115], 0, s[44:45]
	s_mov_b32 m0, s57
	s_nop 0
	global_load_lds_dwordx4 v[114:115], off
	global_load_lds_dwordx4 v[114:115], off offset:1024
	v_lshl_add_u64 v[114:115], v[114:115], 0, s[44:45]
	s_mov_b32 m0, s58
	s_nop 0
	global_load_lds_dwordx4 v[114:115], off
	global_load_lds_dwordx4 v[114:115], off offset:1024
	v_lshl_add_u64 v[96:97], v[96:97], 0, s[86:87]
	v_lshl_add_u64 v[98:99], v[98:99], 0, s[86:87]
	s_waitcnt vmcnt(4)
	s_waitcnt lgkmcnt(0)
	s_barrier
	ds_read_b128 v[134:137], v113
	ds_read_b128 v[142:145], v119 offset:8192
	ds_read_b128 v[146:149], v119 offset:10240
	ds_read_b128 v[150:153], v119 offset:49152
	ds_read_b128 v[154:157], v119 offset:51200
	ds_read_b128 v[138:141], v113 offset:2048
	ds_read_b128 v[158:161], v122
	ds_read_b128 v[166:169], v125 offset:8192
	ds_read_b128 v[244:247], v125 offset:10240
	ds_read_b128 v[250:253], v125 offset:49152
	ds_read_b128 v[162:165], v122 offset:2048
	ds_read_b128 v[128:131], v125 offset:51200
	s_waitcnt lgkmcnt(6)
	v_mfma_f32_32x32x16_bf16 v[32:47], v[134:137], v[142:145], 0
	v_mfma_f32_32x32x16_bf16 v[48:63], v[134:137], v[146:149], 0
	v_mfma_f32_32x32x16_bf16 v[170:185], v[134:137], v[150:153], 0
	v_mfma_f32_32x32x16_bf16 v[186:201], v[134:137], v[154:157], 0
	v_mfma_f32_32x32x16_bf16 v[16:31], v[138:141], v[142:145], 0
	v_mfma_f32_32x32x16_bf16 v[0:15], v[138:141], v[146:149], 0
	v_mfma_f32_32x32x16_bf16 v[202:217], v[138:141], v[150:153], 0
	v_mfma_f32_32x32x16_bf16 v[226:241], v[138:141], v[154:157], 0
	s_waitcnt vmcnt(2)
	s_waitcnt lgkmcnt(0)
	s_barrier
	ds_read_b128 v[134:137], v113 offset:16384
	ds_read_b128 v[142:145], v119 offset:24576
	v_mfma_f32_32x32x16_bf16 v[32:47], v[158:161], v[166:169], v[32:47]
	ds_read_b128 v[146:149], v119 offset:26624
	ds_read_b128 v[150:153], v132 offset:40960
	v_mfma_f32_32x32x16_bf16 v[48:63], v[158:161], v[244:247], v[48:63]
	ds_read_b128 v[154:157], v132 offset:43008
	ds_read_b128 v[138:141], v113 offset:18432
	v_mfma_f32_32x32x16_bf16 v[170:185], v[158:161], v[250:253], v[170:185]
	v_mfma_f32_32x32x16_bf16 v[186:201], v[158:161], v[128:131], v[186:201]
	ds_read_b128 v[158:161], v122 offset:16384
	v_mfma_f32_32x32x16_bf16 v[16:31], v[162:165], v[166:169], v[16:31]
	ds_read_b128 v[166:169], v125 offset:24576
	v_mfma_f32_32x32x16_bf16 v[0:15], v[162:165], v[244:247], v[0:15]
	ds_read_b128 v[244:247], v125 offset:26624
	v_mfma_f32_32x32x16_bf16 v[202:217], v[162:165], v[250:253], v[202:217]
	ds_read_b128 v[250:253], v133 offset:40960
	v_mfma_f32_32x32x16_bf16 v[226:241], v[162:165], v[128:131], v[226:241]
	ds_read_b128 v[162:165], v122 offset:18432
	ds_read_b128 v[128:131], v133 offset:43008
	s_waitcnt lgkmcnt(6)
	v_mfma_f32_32x32x16_bf16 v[32:47], v[134:137], v[142:145], v[32:47]
	s_mov_b32 m0, s50
	v_lshl_add_u64 v[96:97], v[96:97], 0, s[44:45]
	global_load_lds_dwordx4 v[96:97], off
	v_mfma_f32_32x32x16_bf16 v[48:63], v[134:137], v[146:149], v[48:63]
	global_load_lds_dwordx4 v[96:97], off offset:1024
	v_mfma_f32_32x32x16_bf16 v[170:185], v[134:137], v[150:153], v[170:185]
	s_mov_b32 m0, s53
	v_lshl_add_u64 v[98:99], v[98:99], 0, s[44:45]
	global_load_lds_dwordx4 v[98:99], off
	v_mfma_f32_32x32x16_bf16 v[186:201], v[134:137], v[154:157], v[186:201]
	global_load_lds_dwordx4 v[98:99], off offset:1024
	v_mfma_f32_32x32x16_bf16 v[16:31], v[138:141], v[142:145], v[16:31]
	s_mov_b32 m0, s56
	v_lshl_add_u64 v[114:115], v[98:99], 0, s[72:73]
	global_load_lds_dwordx4 v[114:115], off
	v_mfma_f32_32x32x16_bf16 v[0:15], v[138:141], v[146:149], v[0:15]
	global_load_lds_dwordx4 v[114:115], off offset:1024
	v_mfma_f32_32x32x16_bf16 v[202:217], v[138:141], v[150:153], v[202:217]
	v_mfma_f32_32x32x16_bf16 v[226:241], v[138:141], v[154:157], v[226:241]
	s_waitcnt vmcnt(6)
	s_waitcnt lgkmcnt(0)
	s_barrier
	ds_read_b128 v[134:137], v113 offset:32768
	ds_read_b128 v[142:145], v119 offset:40960
	v_mfma_f32_32x32x16_bf16 v[32:47], v[158:161], v[166:169], v[32:47]
	ds_read_b128 v[146:149], v119 offset:43008
	ds_read_b128 v[150:153], v132 offset:57344
	v_mfma_f32_32x32x16_bf16 v[48:63], v[158:161], v[244:247], v[48:63]
	ds_read_b128 v[154:157], v132 offset:59392
	ds_read_b128 v[138:141], v113 offset:34816
	v_mfma_f32_32x32x16_bf16 v[170:185], v[158:161], v[250:253], v[170:185]
	v_mfma_f32_32x32x16_bf16 v[186:201], v[158:161], v[128:131], v[186:201]
	ds_read_b128 v[158:161], v122 offset:32768
	v_mfma_f32_32x32x16_bf16 v[16:31], v[162:165], v[166:169], v[16:31]
	ds_read_b128 v[166:169], v125 offset:40960
	v_mfma_f32_32x32x16_bf16 v[0:15], v[162:165], v[244:247], v[0:15]
	ds_read_b128 v[244:247], v125 offset:43008
	v_mfma_f32_32x32x16_bf16 v[202:217], v[162:165], v[250:253], v[202:217]
	ds_read_b128 v[250:253], v133 offset:57344
	v_mfma_f32_32x32x16_bf16 v[226:241], v[162:165], v[128:131], v[226:241]
	ds_read_b128 v[162:165], v122 offset:34816
	ds_read_b128 v[128:131], v133 offset:59392
	s_waitcnt lgkmcnt(6)
	v_mfma_f32_32x32x16_bf16 v[32:47], v[134:137], v[142:145], v[32:47]
	s_mov_b32 m0, s51
	v_lshl_add_u64 v[96:97], v[96:97], 0, s[44:45]
	global_load_lds_dwordx4 v[96:97], off
	v_mfma_f32_32x32x16_bf16 v[48:63], v[134:137], v[146:149], v[48:63]
	global_load_lds_dwordx4 v[96:97], off offset:1024
	v_mfma_f32_32x32x16_bf16 v[170:185], v[134:137], v[150:153], v[170:185]
	s_mov_b32 m0, s54
	v_lshl_add_u64 v[98:99], v[98:99], 0, s[44:45]
	global_load_lds_dwordx4 v[98:99], off
	v_mfma_f32_32x32x16_bf16 v[186:201], v[134:137], v[154:157], v[186:201]
	global_load_lds_dwordx4 v[98:99], off offset:1024
	v_mfma_f32_32x32x16_bf16 v[16:31], v[138:141], v[142:145], v[16:31]
	s_mov_b32 m0, s57
	v_lshl_add_u64 v[114:115], v[98:99], 0, s[72:73]
	global_load_lds_dwordx4 v[114:115], off
	v_mfma_f32_32x32x16_bf16 v[0:15], v[138:141], v[146:149], v[0:15]
	global_load_lds_dwordx4 v[114:115], off offset:1024
	v_mfma_f32_32x32x16_bf16 v[202:217], v[138:141], v[150:153], v[202:217]
	v_mfma_f32_32x32x16_bf16 v[226:241], v[138:141], v[154:157], v[226:241]
	s_waitcnt vmcnt(6)
	s_waitcnt lgkmcnt(0)
	s_barrier
	ds_read_b128 v[134:137], v113
	ds_read_b128 v[142:145], v119 offset:8192
	v_mfma_f32_32x32x16_bf16 v[32:47], v[158:161], v[166:169], v[32:47]
	ds_read_b128 v[146:149], v119 offset:10240
	ds_read_b128 v[150:153], v119 offset:49152
	v_mfma_f32_32x32x16_bf16 v[48:63], v[158:161], v[244:247], v[48:63]
	ds_read_b128 v[154:157], v119 offset:51200
	ds_read_b128 v[138:141], v113 offset:2048
	v_mfma_f32_32x32x16_bf16 v[170:185], v[158:161], v[250:253], v[170:185]
	v_mfma_f32_32x32x16_bf16 v[186:201], v[158:161], v[128:131], v[186:201]
	ds_read_b128 v[158:161], v122
	v_mfma_f32_32x32x16_bf16 v[16:31], v[162:165], v[166:169], v[16:31]
	ds_read_b128 v[166:169], v125 offset:8192
	v_mfma_f32_32x32x16_bf16 v[0:15], v[162:165], v[244:247], v[0:15]
	ds_read_b128 v[244:247], v125 offset:10240
	v_mfma_f32_32x32x16_bf16 v[202:217], v[162:165], v[250:253], v[202:217]
	ds_read_b128 v[250:253], v125 offset:49152
	v_mfma_f32_32x32x16_bf16 v[226:241], v[162:165], v[128:131], v[226:241]
	ds_read_b128 v[162:165], v122 offset:2048
	ds_read_b128 v[128:131], v125 offset:51200
	s_waitcnt lgkmcnt(6)
	v_mfma_f32_32x32x16_bf16 v[32:47], v[134:137], v[142:145], v[32:47]
	s_mov_b32 m0, s52
	v_lshl_add_u64 v[96:97], v[96:97], 0, s[44:45]
	global_load_lds_dwordx4 v[96:97], off
	v_mfma_f32_32x32x16_bf16 v[48:63], v[134:137], v[146:149], v[48:63]
	global_load_lds_dwordx4 v[96:97], off offset:1024
	v_mfma_f32_32x32x16_bf16 v[170:185], v[134:137], v[150:153], v[170:185]
	s_mov_b32 m0, s55
	v_lshl_add_u64 v[98:99], v[98:99], 0, s[44:45]
	global_load_lds_dwordx4 v[98:99], off
	v_mfma_f32_32x32x16_bf16 v[186:201], v[134:137], v[154:157], v[186:201]
	global_load_lds_dwordx4 v[98:99], off offset:1024
	v_mfma_f32_32x32x16_bf16 v[16:31], v[138:141], v[142:145], v[16:31]
	s_mov_b32 m0, s58
	v_lshl_add_u64 v[114:115], v[98:99], 0, s[72:73]
	global_load_lds_dwordx4 v[114:115], off
	v_mfma_f32_32x32x16_bf16 v[0:15], v[138:141], v[146:149], v[0:15]
	global_load_lds_dwordx4 v[114:115], off offset:1024
	v_mfma_f32_32x32x16_bf16 v[202:217], v[138:141], v[150:153], v[202:217]
	v_mfma_f32_32x32x16_bf16 v[226:241], v[138:141], v[154:157], v[226:241]
	s_waitcnt vmcnt(6)
	s_waitcnt lgkmcnt(0)
	s_barrier
	ds_read_b128 v[134:137], v113 offset:16384
	ds_read_b128 v[142:145], v119 offset:24576
	v_mfma_f32_32x32x16_bf16 v[32:47], v[158:161], v[166:169], v[32:47]
	ds_read_b128 v[146:149], v119 offset:26624
	ds_read_b128 v[150:153], v132 offset:40960
	v_mfma_f32_32x32x16_bf16 v[48:63], v[158:161], v[244:247], v[48:63]
	ds_read_b128 v[154:157], v132 offset:43008
	ds_read_b128 v[138:141], v113 offset:18432
	v_mfma_f32_32x32x16_bf16 v[170:185], v[158:161], v[250:253], v[170:185]
	v_mfma_f32_32x32x16_bf16 v[186:201], v[158:161], v[128:131], v[186:201]
	ds_read_b128 v[158:161], v122 offset:16384
	v_mfma_f32_32x32x16_bf16 v[16:31], v[162:165], v[166:169], v[16:31]
	ds_read_b128 v[166:169], v125 offset:24576
	v_mfma_f32_32x32x16_bf16 v[0:15], v[162:165], v[244:247], v[0:15]
	ds_read_b128 v[244:247], v125 offset:26624
	v_mfma_f32_32x32x16_bf16 v[202:217], v[162:165], v[250:253], v[202:217]
	ds_read_b128 v[250:253], v133 offset:40960
	v_mfma_f32_32x32x16_bf16 v[226:241], v[162:165], v[128:131], v[226:241]
	ds_read_b128 v[162:165], v122 offset:18432
	ds_read_b128 v[128:131], v133 offset:43008
	s_waitcnt lgkmcnt(6)
	v_mfma_f32_32x32x16_bf16 v[32:47], v[134:137], v[142:145], v[32:47]
	s_mov_b32 m0, s50
	v_lshl_add_u64 v[96:97], v[96:97], 0, s[44:45]
	global_load_lds_dwordx4 v[96:97], off
	v_mfma_f32_32x32x16_bf16 v[48:63], v[134:137], v[146:149], v[48:63]
	global_load_lds_dwordx4 v[96:97], off offset:1024
	v_mfma_f32_32x32x16_bf16 v[170:185], v[134:137], v[150:153], v[170:185]
	s_mov_b32 m0, s53
	v_lshl_add_u64 v[98:99], v[98:99], 0, s[44:45]
	global_load_lds_dwordx4 v[98:99], off
	v_mfma_f32_32x32x16_bf16 v[186:201], v[134:137], v[154:157], v[186:201]
	global_load_lds_dwordx4 v[98:99], off offset:1024
	v_mfma_f32_32x32x16_bf16 v[16:31], v[138:141], v[142:145], v[16:31]
	s_mov_b32 m0, s56
	v_lshl_add_u64 v[114:115], v[98:99], 0, s[72:73]
	global_load_lds_dwordx4 v[114:115], off
	v_mfma_f32_32x32x16_bf16 v[0:15], v[138:141], v[146:149], v[0:15]
	global_load_lds_dwordx4 v[114:115], off offset:1024
	v_mfma_f32_32x32x16_bf16 v[202:217], v[138:141], v[150:153], v[202:217]
	v_mfma_f32_32x32x16_bf16 v[226:241], v[138:141], v[154:157], v[226:241]
	s_waitcnt vmcnt(6)
	s_waitcnt lgkmcnt(0)
	s_barrier
	ds_read_b128 v[134:137], v113 offset:32768
	ds_read_b128 v[142:145], v119 offset:40960
	v_mfma_f32_32x32x16_bf16 v[32:47], v[158:161], v[166:169], v[32:47]
	ds_read_b128 v[146:149], v119 offset:43008
	ds_read_b128 v[150:153], v132 offset:57344
	v_mfma_f32_32x32x16_bf16 v[48:63], v[158:161], v[244:247], v[48:63]
	ds_read_b128 v[154:157], v132 offset:59392
	ds_read_b128 v[138:141], v113 offset:34816
	v_mfma_f32_32x32x16_bf16 v[170:185], v[158:161], v[250:253], v[170:185]
	v_mfma_f32_32x32x16_bf16 v[186:201], v[158:161], v[128:131], v[186:201]
	ds_read_b128 v[158:161], v122 offset:32768
	v_mfma_f32_32x32x16_bf16 v[16:31], v[162:165], v[166:169], v[16:31]
	ds_read_b128 v[166:169], v125 offset:40960
	v_mfma_f32_32x32x16_bf16 v[0:15], v[162:165], v[244:247], v[0:15]
	ds_read_b128 v[244:247], v125 offset:43008
	v_mfma_f32_32x32x16_bf16 v[202:217], v[162:165], v[250:253], v[202:217]
	ds_read_b128 v[250:253], v133 offset:57344
	v_mfma_f32_32x32x16_bf16 v[226:241], v[162:165], v[128:131], v[226:241]
	ds_read_b128 v[162:165], v122 offset:34816
	ds_read_b128 v[128:131], v133 offset:59392
	s_waitcnt lgkmcnt(6)
	v_mfma_f32_32x32x16_bf16 v[32:47], v[134:137], v[142:145], v[32:47]
	s_mov_b32 m0, s51
	v_lshl_add_u64 v[96:97], v[96:97], 0, s[44:45]
	global_load_lds_dwordx4 v[96:97], off
	v_mfma_f32_32x32x16_bf16 v[48:63], v[134:137], v[146:149], v[48:63]
	global_load_lds_dwordx4 v[96:97], off offset:1024
	v_mfma_f32_32x32x16_bf16 v[170:185], v[134:137], v[150:153], v[170:185]
	s_mov_b32 m0, s54
	v_lshl_add_u64 v[98:99], v[98:99], 0, s[44:45]
	global_load_lds_dwordx4 v[98:99], off
	v_mfma_f32_32x32x16_bf16 v[186:201], v[134:137], v[154:157], v[186:201]
	global_load_lds_dwordx4 v[98:99], off offset:1024
	v_mfma_f32_32x32x16_bf16 v[16:31], v[138:141], v[142:145], v[16:31]
	s_mov_b32 m0, s57
	v_lshl_add_u64 v[114:115], v[98:99], 0, s[72:73]
	global_load_lds_dwordx4 v[114:115], off
	v_mfma_f32_32x32x16_bf16 v[0:15], v[138:141], v[146:149], v[0:15]
	global_load_lds_dwordx4 v[114:115], off offset:1024
	v_mfma_f32_32x32x16_bf16 v[202:217], v[138:141], v[150:153], v[202:217]
	v_mfma_f32_32x32x16_bf16 v[226:241], v[138:141], v[154:157], v[226:241]
	s_waitcnt vmcnt(6)
	s_waitcnt lgkmcnt(0)
	s_barrier
	ds_read_b128 v[134:137], v113
	ds_read_b128 v[142:145], v119 offset:8192
	v_mfma_f32_32x32x16_bf16 v[32:47], v[158:161], v[166:169], v[32:47]
	ds_read_b128 v[146:149], v119 offset:10240
	ds_read_b128 v[150:153], v119 offset:49152
	v_mfma_f32_32x32x16_bf16 v[48:63], v[158:161], v[244:247], v[48:63]
	ds_read_b128 v[154:157], v119 offset:51200
	ds_read_b128 v[138:141], v113 offset:2048
	v_mfma_f32_32x32x16_bf16 v[170:185], v[158:161], v[250:253], v[170:185]
	v_mfma_f32_32x32x16_bf16 v[186:201], v[158:161], v[128:131], v[186:201]
	ds_read_b128 v[158:161], v122
	v_mfma_f32_32x32x16_bf16 v[16:31], v[162:165], v[166:169], v[16:31]
	ds_read_b128 v[166:169], v125 offset:8192
	v_mfma_f32_32x32x16_bf16 v[0:15], v[162:165], v[244:247], v[0:15]
	ds_read_b128 v[244:247], v125 offset:10240
	v_mfma_f32_32x32x16_bf16 v[202:217], v[162:165], v[250:253], v[202:217]
	ds_read_b128 v[250:253], v125 offset:49152
	v_mfma_f32_32x32x16_bf16 v[226:241], v[162:165], v[128:131], v[226:241]
	ds_read_b128 v[162:165], v122 offset:2048
	ds_read_b128 v[128:131], v125 offset:51200
	s_waitcnt lgkmcnt(6)
	v_mfma_f32_32x32x16_bf16 v[32:47], v[134:137], v[142:145], v[32:47]
	s_mov_b32 m0, s52
	v_lshl_add_u64 v[96:97], v[96:97], 0, s[44:45]
	global_load_lds_dwordx4 v[96:97], off
	v_mfma_f32_32x32x16_bf16 v[48:63], v[134:137], v[146:149], v[48:63]
	global_load_lds_dwordx4 v[96:97], off offset:1024
	v_mfma_f32_32x32x16_bf16 v[170:185], v[134:137], v[150:153], v[170:185]
	s_mov_b32 m0, s55
	v_lshl_add_u64 v[98:99], v[98:99], 0, s[44:45]
	global_load_lds_dwordx4 v[98:99], off
	v_mfma_f32_32x32x16_bf16 v[186:201], v[134:137], v[154:157], v[186:201]
	global_load_lds_dwordx4 v[98:99], off offset:1024
	v_mfma_f32_32x32x16_bf16 v[16:31], v[138:141], v[142:145], v[16:31]
	s_mov_b32 m0, s58
	v_lshl_add_u64 v[114:115], v[98:99], 0, s[72:73]
	global_load_lds_dwordx4 v[114:115], off
	v_mfma_f32_32x32x16_bf16 v[0:15], v[138:141], v[146:149], v[0:15]
	global_load_lds_dwordx4 v[114:115], off offset:1024
	v_mfma_f32_32x32x16_bf16 v[202:217], v[138:141], v[150:153], v[202:217]
	v_mfma_f32_32x32x16_bf16 v[226:241], v[138:141], v[154:157], v[226:241]
	s_waitcnt vmcnt(6)
	s_waitcnt lgkmcnt(0)
	s_barrier
	ds_read_b128 v[134:137], v113 offset:16384
	ds_read_b128 v[142:145], v119 offset:24576
	v_mfma_f32_32x32x16_bf16 v[32:47], v[158:161], v[166:169], v[32:47]
	ds_read_b128 v[146:149], v119 offset:26624
	ds_read_b128 v[150:153], v132 offset:40960
	v_mfma_f32_32x32x16_bf16 v[48:63], v[158:161], v[244:247], v[48:63]
	ds_read_b128 v[154:157], v132 offset:43008
	ds_read_b128 v[138:141], v113 offset:18432
	v_mfma_f32_32x32x16_bf16 v[170:185], v[158:161], v[250:253], v[170:185]
	v_mfma_f32_32x32x16_bf16 v[186:201], v[158:161], v[128:131], v[186:201]
	ds_read_b128 v[158:161], v122 offset:16384
	v_mfma_f32_32x32x16_bf16 v[16:31], v[162:165], v[166:169], v[16:31]
	ds_read_b128 v[166:169], v125 offset:24576
	v_mfma_f32_32x32x16_bf16 v[0:15], v[162:165], v[244:247], v[0:15]
	ds_read_b128 v[244:247], v125 offset:26624
	v_mfma_f32_32x32x16_bf16 v[202:217], v[162:165], v[250:253], v[202:217]
	ds_read_b128 v[250:253], v133 offset:40960
	v_mfma_f32_32x32x16_bf16 v[226:241], v[162:165], v[128:131], v[226:241]
	ds_read_b128 v[162:165], v122 offset:18432
	ds_read_b128 v[128:131], v133 offset:43008
	s_waitcnt lgkmcnt(6)
	v_mfma_f32_32x32x16_bf16 v[32:47], v[134:137], v[142:145], v[32:47]
	s_mov_b32 m0, s50
	v_lshl_add_u64 v[96:97], v[96:97], 0, s[44:45]
	global_load_lds_dwordx4 v[96:97], off
	v_mfma_f32_32x32x16_bf16 v[48:63], v[134:137], v[146:149], v[48:63]
	global_load_lds_dwordx4 v[96:97], off offset:1024
	v_mfma_f32_32x32x16_bf16 v[170:185], v[134:137], v[150:153], v[170:185]
	s_mov_b32 m0, s53
	v_lshl_add_u64 v[98:99], v[98:99], 0, s[44:45]
	global_load_lds_dwordx4 v[98:99], off
	v_mfma_f32_32x32x16_bf16 v[186:201], v[134:137], v[154:157], v[186:201]
	global_load_lds_dwordx4 v[98:99], off offset:1024
	v_mfma_f32_32x32x16_bf16 v[16:31], v[138:141], v[142:145], v[16:31]
	s_mov_b32 m0, s56
	v_lshl_add_u64 v[114:115], v[98:99], 0, s[72:73]
	global_load_lds_dwordx4 v[114:115], off
	v_mfma_f32_32x32x16_bf16 v[0:15], v[138:141], v[146:149], v[0:15]
	global_load_lds_dwordx4 v[114:115], off offset:1024
	v_mfma_f32_32x32x16_bf16 v[202:217], v[138:141], v[150:153], v[202:217]
	v_mfma_f32_32x32x16_bf16 v[226:241], v[138:141], v[154:157], v[226:241]
	s_waitcnt vmcnt(6)
	s_waitcnt lgkmcnt(0)
	s_barrier
	ds_read_b128 v[134:137], v113 offset:32768
	ds_read_b128 v[142:145], v119 offset:40960
	v_mfma_f32_32x32x16_bf16 v[32:47], v[158:161], v[166:169], v[32:47]
	ds_read_b128 v[146:149], v119 offset:43008
	ds_read_b128 v[150:153], v132 offset:57344
	v_mfma_f32_32x32x16_bf16 v[48:63], v[158:161], v[244:247], v[48:63]
	ds_read_b128 v[154:157], v132 offset:59392
	ds_read_b128 v[138:141], v113 offset:34816
	v_mfma_f32_32x32x16_bf16 v[170:185], v[158:161], v[250:253], v[170:185]
	v_mfma_f32_32x32x16_bf16 v[186:201], v[158:161], v[128:131], v[186:201]
	ds_read_b128 v[158:161], v122 offset:32768
	v_mfma_f32_32x32x16_bf16 v[16:31], v[162:165], v[166:169], v[16:31]
	ds_read_b128 v[166:169], v125 offset:40960
	v_mfma_f32_32x32x16_bf16 v[0:15], v[162:165], v[244:247], v[0:15]
	ds_read_b128 v[244:247], v125 offset:43008
	v_mfma_f32_32x32x16_bf16 v[202:217], v[162:165], v[250:253], v[202:217]
	ds_read_b128 v[250:253], v133 offset:57344
	v_mfma_f32_32x32x16_bf16 v[226:241], v[162:165], v[128:131], v[226:241]
	ds_read_b128 v[162:165], v122 offset:34816
	ds_read_b128 v[128:131], v133 offset:59392
	s_waitcnt lgkmcnt(6)
	v_mfma_f32_32x32x16_bf16 v[32:47], v[134:137], v[142:145], v[32:47]
	s_mov_b32 m0, s51
	v_lshl_add_u64 v[96:97], v[96:97], 0, s[44:45]
	global_load_lds_dwordx4 v[96:97], off
	v_mfma_f32_32x32x16_bf16 v[48:63], v[134:137], v[146:149], v[48:63]
	global_load_lds_dwordx4 v[96:97], off offset:1024
	v_mfma_f32_32x32x16_bf16 v[170:185], v[134:137], v[150:153], v[170:185]
	s_mov_b32 m0, s54
	v_lshl_add_u64 v[98:99], v[98:99], 0, s[44:45]
	global_load_lds_dwordx4 v[98:99], off
	v_mfma_f32_32x32x16_bf16 v[186:201], v[134:137], v[154:157], v[186:201]
	global_load_lds_dwordx4 v[98:99], off offset:1024
	v_mfma_f32_32x32x16_bf16 v[16:31], v[138:141], v[142:145], v[16:31]
	s_mov_b32 m0, s57
	v_lshl_add_u64 v[114:115], v[98:99], 0, s[72:73]
	global_load_lds_dwordx4 v[114:115], off
	v_mfma_f32_32x32x16_bf16 v[0:15], v[138:141], v[146:149], v[0:15]
	global_load_lds_dwordx4 v[114:115], off offset:1024
	v_mfma_f32_32x32x16_bf16 v[202:217], v[138:141], v[150:153], v[202:217]
	v_mfma_f32_32x32x16_bf16 v[226:241], v[138:141], v[154:157], v[226:241]
	s_waitcnt vmcnt(6)
	s_waitcnt lgkmcnt(0)
	s_barrier
	ds_read_b128 v[134:137], v113
	ds_read_b128 v[142:145], v119 offset:8192
	v_mfma_f32_32x32x16_bf16 v[32:47], v[158:161], v[166:169], v[32:47]
	ds_read_b128 v[146:149], v119 offset:10240
	ds_read_b128 v[150:153], v119 offset:49152
	v_mfma_f32_32x32x16_bf16 v[48:63], v[158:161], v[244:247], v[48:63]
	ds_read_b128 v[154:157], v119 offset:51200
	ds_read_b128 v[138:141], v113 offset:2048
	v_mfma_f32_32x32x16_bf16 v[170:185], v[158:161], v[250:253], v[170:185]
	v_mfma_f32_32x32x16_bf16 v[186:201], v[158:161], v[128:131], v[186:201]
	ds_read_b128 v[158:161], v122
	v_mfma_f32_32x32x16_bf16 v[16:31], v[162:165], v[166:169], v[16:31]
	ds_read_b128 v[166:169], v125 offset:8192
	v_mfma_f32_32x32x16_bf16 v[0:15], v[162:165], v[244:247], v[0:15]
	ds_read_b128 v[244:247], v125 offset:10240
	v_mfma_f32_32x32x16_bf16 v[202:217], v[162:165], v[250:253], v[202:217]
	ds_read_b128 v[250:253], v125 offset:49152
	v_mfma_f32_32x32x16_bf16 v[226:241], v[162:165], v[128:131], v[226:241]
	ds_read_b128 v[162:165], v122 offset:2048
	ds_read_b128 v[128:131], v125 offset:51200
	s_waitcnt lgkmcnt(6)
	v_mfma_f32_32x32x16_bf16 v[32:47], v[134:137], v[142:145], v[32:47]
	s_mov_b32 m0, s52
	v_lshl_add_u64 v[96:97], v[96:97], 0, s[44:45]
	global_load_lds_dwordx4 v[96:97], off
	v_mfma_f32_32x32x16_bf16 v[48:63], v[134:137], v[146:149], v[48:63]
	global_load_lds_dwordx4 v[96:97], off offset:1024
	v_mfma_f32_32x32x16_bf16 v[170:185], v[134:137], v[150:153], v[170:185]
	s_mov_b32 m0, s55
	v_lshl_add_u64 v[98:99], v[98:99], 0, s[44:45]
	global_load_lds_dwordx4 v[98:99], off
	v_mfma_f32_32x32x16_bf16 v[186:201], v[134:137], v[154:157], v[186:201]
	global_load_lds_dwordx4 v[98:99], off offset:1024
	v_mfma_f32_32x32x16_bf16 v[16:31], v[138:141], v[142:145], v[16:31]
	s_mov_b32 m0, s58
	v_lshl_add_u64 v[114:115], v[98:99], 0, s[72:73]
	global_load_lds_dwordx4 v[114:115], off
	v_mfma_f32_32x32x16_bf16 v[0:15], v[138:141], v[146:149], v[0:15]
	global_load_lds_dwordx4 v[114:115], off offset:1024
	v_mfma_f32_32x32x16_bf16 v[202:217], v[138:141], v[150:153], v[202:217]
	v_mfma_f32_32x32x16_bf16 v[226:241], v[138:141], v[154:157], v[226:241]
	s_waitcnt vmcnt(6)
	s_waitcnt lgkmcnt(0)
	s_barrier
	ds_read_b128 v[134:137], v113 offset:16384
	ds_read_b128 v[142:145], v119 offset:24576
	v_mfma_f32_32x32x16_bf16 v[32:47], v[158:161], v[166:169], v[32:47]
	ds_read_b128 v[146:149], v119 offset:26624
	ds_read_b128 v[150:153], v132 offset:40960
	v_mfma_f32_32x32x16_bf16 v[48:63], v[158:161], v[244:247], v[48:63]
	ds_read_b128 v[154:157], v132 offset:43008
	ds_read_b128 v[138:141], v113 offset:18432
	v_mfma_f32_32x32x16_bf16 v[170:185], v[158:161], v[250:253], v[170:185]
	v_mfma_f32_32x32x16_bf16 v[186:201], v[158:161], v[128:131], v[186:201]
	ds_read_b128 v[158:161], v122 offset:16384
	v_mfma_f32_32x32x16_bf16 v[16:31], v[162:165], v[166:169], v[16:31]
	ds_read_b128 v[166:169], v125 offset:24576
	v_mfma_f32_32x32x16_bf16 v[0:15], v[162:165], v[244:247], v[0:15]
	ds_read_b128 v[244:247], v125 offset:26624
	v_mfma_f32_32x32x16_bf16 v[202:217], v[162:165], v[250:253], v[202:217]
	ds_read_b128 v[250:253], v133 offset:40960
	v_mfma_f32_32x32x16_bf16 v[226:241], v[162:165], v[128:131], v[226:241]
	ds_read_b128 v[162:165], v122 offset:18432
	ds_read_b128 v[128:131], v133 offset:43008
	s_waitcnt lgkmcnt(6)
	v_mfma_f32_32x32x16_bf16 v[32:47], v[134:137], v[142:145], v[32:47]
	s_mov_b32 m0, s50
	v_lshl_add_u64 v[96:97], v[96:97], 0, s[44:45]
	global_load_lds_dwordx4 v[96:97], off
	v_mfma_f32_32x32x16_bf16 v[48:63], v[134:137], v[146:149], v[48:63]
	global_load_lds_dwordx4 v[96:97], off offset:1024
	v_mfma_f32_32x32x16_bf16 v[170:185], v[134:137], v[150:153], v[170:185]
	s_mov_b32 m0, s53
	v_lshl_add_u64 v[98:99], v[98:99], 0, s[44:45]
	global_load_lds_dwordx4 v[98:99], off
	v_mfma_f32_32x32x16_bf16 v[186:201], v[134:137], v[154:157], v[186:201]
	global_load_lds_dwordx4 v[98:99], off offset:1024
	v_mfma_f32_32x32x16_bf16 v[16:31], v[138:141], v[142:145], v[16:31]
	s_mov_b32 m0, s56
	v_lshl_add_u64 v[114:115], v[98:99], 0, s[72:73]
	global_load_lds_dwordx4 v[114:115], off
	v_mfma_f32_32x32x16_bf16 v[0:15], v[138:141], v[146:149], v[0:15]
	global_load_lds_dwordx4 v[114:115], off offset:1024
	v_mfma_f32_32x32x16_bf16 v[202:217], v[138:141], v[150:153], v[202:217]
	v_mfma_f32_32x32x16_bf16 v[226:241], v[138:141], v[154:157], v[226:241]
	s_waitcnt vmcnt(6)
	s_waitcnt lgkmcnt(0)
	s_barrier
	ds_read_b128 v[134:137], v113 offset:32768
	ds_read_b128 v[142:145], v119 offset:40960
	v_mfma_f32_32x32x16_bf16 v[32:47], v[158:161], v[166:169], v[32:47]
	ds_read_b128 v[146:149], v119 offset:43008
	ds_read_b128 v[150:153], v132 offset:57344
	v_mfma_f32_32x32x16_bf16 v[48:63], v[158:161], v[244:247], v[48:63]
	ds_read_b128 v[154:157], v132 offset:59392
	ds_read_b128 v[138:141], v113 offset:34816
	v_mfma_f32_32x32x16_bf16 v[170:185], v[158:161], v[250:253], v[170:185]
	v_mfma_f32_32x32x16_bf16 v[186:201], v[158:161], v[128:131], v[186:201]
	ds_read_b128 v[158:161], v122 offset:32768
	v_mfma_f32_32x32x16_bf16 v[16:31], v[162:165], v[166:169], v[16:31]
	ds_read_b128 v[166:169], v125 offset:40960
	v_mfma_f32_32x32x16_bf16 v[0:15], v[162:165], v[244:247], v[0:15]
	ds_read_b128 v[244:247], v125 offset:43008
	v_mfma_f32_32x32x16_bf16 v[202:217], v[162:165], v[250:253], v[202:217]
	ds_read_b128 v[250:253], v133 offset:57344
	v_mfma_f32_32x32x16_bf16 v[226:241], v[162:165], v[128:131], v[226:241]
	ds_read_b128 v[162:165], v122 offset:34816
	ds_read_b128 v[128:131], v133 offset:59392
	s_waitcnt lgkmcnt(6)
	v_mfma_f32_32x32x16_bf16 v[32:47], v[134:137], v[142:145], v[32:47]
	s_mov_b32 m0, s51
	v_lshl_add_u64 v[96:97], v[96:97], 0, s[44:45]
	global_load_lds_dwordx4 v[96:97], off
	v_mfma_f32_32x32x16_bf16 v[48:63], v[134:137], v[146:149], v[48:63]
	global_load_lds_dwordx4 v[96:97], off offset:1024
	v_mfma_f32_32x32x16_bf16 v[170:185], v[134:137], v[150:153], v[170:185]
	s_mov_b32 m0, s54
	v_lshl_add_u64 v[98:99], v[98:99], 0, s[44:45]
	global_load_lds_dwordx4 v[98:99], off
	v_mfma_f32_32x32x16_bf16 v[186:201], v[134:137], v[154:157], v[186:201]
	global_load_lds_dwordx4 v[98:99], off offset:1024
	v_mfma_f32_32x32x16_bf16 v[16:31], v[138:141], v[142:145], v[16:31]
	s_mov_b32 m0, s57
	v_lshl_add_u64 v[114:115], v[98:99], 0, s[72:73]
	global_load_lds_dwordx4 v[114:115], off
	v_mfma_f32_32x32x16_bf16 v[0:15], v[138:141], v[146:149], v[0:15]
	global_load_lds_dwordx4 v[114:115], off offset:1024
	v_mfma_f32_32x32x16_bf16 v[202:217], v[138:141], v[150:153], v[202:217]
	v_mfma_f32_32x32x16_bf16 v[226:241], v[138:141], v[154:157], v[226:241]
	s_waitcnt vmcnt(6)
	s_waitcnt lgkmcnt(0)
	s_barrier
	ds_read_b128 v[134:137], v113
	ds_read_b128 v[142:145], v119 offset:8192
	v_mfma_f32_32x32x16_bf16 v[32:47], v[158:161], v[166:169], v[32:47]
	ds_read_b128 v[146:149], v119 offset:10240
	ds_read_b128 v[150:153], v119 offset:49152
	v_mfma_f32_32x32x16_bf16 v[48:63], v[158:161], v[244:247], v[48:63]
	ds_read_b128 v[154:157], v119 offset:51200
	ds_read_b128 v[138:141], v113 offset:2048
	v_mfma_f32_32x32x16_bf16 v[170:185], v[158:161], v[250:253], v[170:185]
	v_mfma_f32_32x32x16_bf16 v[186:201], v[158:161], v[128:131], v[186:201]
	ds_read_b128 v[158:161], v122
	v_mfma_f32_32x32x16_bf16 v[16:31], v[162:165], v[166:169], v[16:31]
	ds_read_b128 v[166:169], v125 offset:8192
	v_mfma_f32_32x32x16_bf16 v[0:15], v[162:165], v[244:247], v[0:15]
	ds_read_b128 v[244:247], v125 offset:10240
	v_mfma_f32_32x32x16_bf16 v[202:217], v[162:165], v[250:253], v[202:217]
	ds_read_b128 v[250:253], v125 offset:49152
	v_mfma_f32_32x32x16_bf16 v[226:241], v[162:165], v[128:131], v[226:241]
	ds_read_b128 v[162:165], v122 offset:2048
	ds_read_b128 v[128:131], v125 offset:51200
	s_waitcnt lgkmcnt(6)
	v_mfma_f32_32x32x16_bf16 v[32:47], v[134:137], v[142:145], v[32:47]
	s_mov_b32 m0, s52
	v_lshl_add_u64 v[96:97], v[96:97], 0, s[44:45]
	global_load_lds_dwordx4 v[96:97], off
	v_mfma_f32_32x32x16_bf16 v[48:63], v[134:137], v[146:149], v[48:63]
	global_load_lds_dwordx4 v[96:97], off offset:1024
	v_mfma_f32_32x32x16_bf16 v[170:185], v[134:137], v[150:153], v[170:185]
	s_mov_b32 m0, s55
	v_lshl_add_u64 v[98:99], v[98:99], 0, s[44:45]
	global_load_lds_dwordx4 v[98:99], off
	v_mfma_f32_32x32x16_bf16 v[186:201], v[134:137], v[154:157], v[186:201]
	global_load_lds_dwordx4 v[98:99], off offset:1024
	v_mfma_f32_32x32x16_bf16 v[16:31], v[138:141], v[142:145], v[16:31]
	s_mov_b32 m0, s58
	v_lshl_add_u64 v[114:115], v[98:99], 0, s[72:73]
	global_load_lds_dwordx4 v[114:115], off
	v_mfma_f32_32x32x16_bf16 v[0:15], v[138:141], v[146:149], v[0:15]
	global_load_lds_dwordx4 v[114:115], off offset:1024
	v_mfma_f32_32x32x16_bf16 v[202:217], v[138:141], v[150:153], v[202:217]
	v_mfma_f32_32x32x16_bf16 v[226:241], v[138:141], v[154:157], v[226:241]
	s_waitcnt vmcnt(6)
	s_waitcnt lgkmcnt(0)
	s_barrier
	ds_read_b128 v[134:137], v113 offset:16384
	ds_read_b128 v[142:145], v119 offset:24576
	v_mfma_f32_32x32x16_bf16 v[32:47], v[158:161], v[166:169], v[32:47]
	ds_read_b128 v[146:149], v119 offset:26624
	ds_read_b128 v[150:153], v132 offset:40960
	v_mfma_f32_32x32x16_bf16 v[48:63], v[158:161], v[244:247], v[48:63]
	ds_read_b128 v[154:157], v132 offset:43008
	ds_read_b128 v[138:141], v113 offset:18432
	v_mfma_f32_32x32x16_bf16 v[170:185], v[158:161], v[250:253], v[170:185]
	v_mfma_f32_32x32x16_bf16 v[186:201], v[158:161], v[128:131], v[186:201]
	ds_read_b128 v[158:161], v122 offset:16384
	v_mfma_f32_32x32x16_bf16 v[16:31], v[162:165], v[166:169], v[16:31]
	ds_read_b128 v[166:169], v125 offset:24576
	v_mfma_f32_32x32x16_bf16 v[0:15], v[162:165], v[244:247], v[0:15]
	ds_read_b128 v[244:247], v125 offset:26624
	v_mfma_f32_32x32x16_bf16 v[202:217], v[162:165], v[250:253], v[202:217]
	ds_read_b128 v[250:253], v133 offset:40960
	v_mfma_f32_32x32x16_bf16 v[226:241], v[162:165], v[128:131], v[226:241]
	ds_read_b128 v[162:165], v122 offset:18432
	ds_read_b128 v[128:131], v133 offset:43008
	s_waitcnt lgkmcnt(6)
	v_mfma_f32_32x32x16_bf16 v[32:47], v[134:137], v[142:145], v[32:47]
	s_mov_b32 m0, s50
	v_lshl_add_u64 v[96:97], v[96:97], 0, s[44:45]
	global_load_lds_dwordx4 v[96:97], off
	v_mfma_f32_32x32x16_bf16 v[48:63], v[134:137], v[146:149], v[48:63]
	global_load_lds_dwordx4 v[96:97], off offset:1024
	v_mfma_f32_32x32x16_bf16 v[170:185], v[134:137], v[150:153], v[170:185]
	s_mov_b32 m0, s53
	v_lshl_add_u64 v[98:99], v[98:99], 0, s[44:45]
	global_load_lds_dwordx4 v[98:99], off
	v_mfma_f32_32x32x16_bf16 v[186:201], v[134:137], v[154:157], v[186:201]
	global_load_lds_dwordx4 v[98:99], off offset:1024
	v_mfma_f32_32x32x16_bf16 v[16:31], v[138:141], v[142:145], v[16:31]
	s_mov_b32 m0, s56
	v_lshl_add_u64 v[114:115], v[98:99], 0, s[72:73]
	global_load_lds_dwordx4 v[114:115], off
	v_mfma_f32_32x32x16_bf16 v[0:15], v[138:141], v[146:149], v[0:15]
	global_load_lds_dwordx4 v[114:115], off offset:1024
	v_mfma_f32_32x32x16_bf16 v[202:217], v[138:141], v[150:153], v[202:217]
	v_mfma_f32_32x32x16_bf16 v[226:241], v[138:141], v[154:157], v[226:241]
	s_waitcnt vmcnt(6)
	s_waitcnt lgkmcnt(0)
	s_barrier
	ds_read_b128 v[134:137], v113 offset:32768
	ds_read_b128 v[142:145], v119 offset:40960
	v_mfma_f32_32x32x16_bf16 v[32:47], v[158:161], v[166:169], v[32:47]
	ds_read_b128 v[146:149], v119 offset:43008
	ds_read_b128 v[150:153], v132 offset:57344
	v_mfma_f32_32x32x16_bf16 v[48:63], v[158:161], v[244:247], v[48:63]
	ds_read_b128 v[154:157], v132 offset:59392
	ds_read_b128 v[138:141], v113 offset:34816
	v_mfma_f32_32x32x16_bf16 v[170:185], v[158:161], v[250:253], v[170:185]
	v_mfma_f32_32x32x16_bf16 v[186:201], v[158:161], v[128:131], v[186:201]
	ds_read_b128 v[158:161], v122 offset:32768
	v_mfma_f32_32x32x16_bf16 v[16:31], v[162:165], v[166:169], v[16:31]
	ds_read_b128 v[166:169], v125 offset:40960
	v_mfma_f32_32x32x16_bf16 v[0:15], v[162:165], v[244:247], v[0:15]
	ds_read_b128 v[244:247], v125 offset:43008
	v_mfma_f32_32x32x16_bf16 v[202:217], v[162:165], v[250:253], v[202:217]
	ds_read_b128 v[250:253], v133 offset:57344
	v_mfma_f32_32x32x16_bf16 v[226:241], v[162:165], v[128:131], v[226:241]
	ds_read_b128 v[162:165], v122 offset:34816
	ds_read_b128 v[128:131], v133 offset:59392
	s_waitcnt lgkmcnt(6)
	v_mfma_f32_32x32x16_bf16 v[32:47], v[134:137], v[142:145], v[32:47]
	s_mov_b32 m0, s51
	v_lshl_add_u64 v[96:97], v[96:97], 0, s[44:45]
	global_load_lds_dwordx4 v[96:97], off
	v_mfma_f32_32x32x16_bf16 v[48:63], v[134:137], v[146:149], v[48:63]
	global_load_lds_dwordx4 v[96:97], off offset:1024
	v_mfma_f32_32x32x16_bf16 v[170:185], v[134:137], v[150:153], v[170:185]
	s_mov_b32 m0, s54
	v_lshl_add_u64 v[98:99], v[98:99], 0, s[44:45]
	global_load_lds_dwordx4 v[98:99], off
	v_mfma_f32_32x32x16_bf16 v[186:201], v[134:137], v[154:157], v[186:201]
	global_load_lds_dwordx4 v[98:99], off offset:1024
	v_mfma_f32_32x32x16_bf16 v[16:31], v[138:141], v[142:145], v[16:31]
	s_mov_b32 m0, s57
	v_lshl_add_u64 v[114:115], v[98:99], 0, s[72:73]
	global_load_lds_dwordx4 v[114:115], off
	v_mfma_f32_32x32x16_bf16 v[0:15], v[138:141], v[146:149], v[0:15]
	global_load_lds_dwordx4 v[114:115], off offset:1024
	v_mfma_f32_32x32x16_bf16 v[202:217], v[138:141], v[150:153], v[202:217]
	v_mfma_f32_32x32x16_bf16 v[226:241], v[138:141], v[154:157], v[226:241]
	s_waitcnt vmcnt(6)
	s_waitcnt lgkmcnt(0)
	s_barrier
	ds_read_b128 v[134:137], v113
	ds_read_b128 v[142:145], v119 offset:8192
	v_mfma_f32_32x32x16_bf16 v[32:47], v[158:161], v[166:169], v[32:47]
	ds_read_b128 v[146:149], v119 offset:10240
	ds_read_b128 v[150:153], v119 offset:49152
	v_mfma_f32_32x32x16_bf16 v[48:63], v[158:161], v[244:247], v[48:63]
	ds_read_b128 v[154:157], v119 offset:51200
	ds_read_b128 v[138:141], v113 offset:2048
	v_mfma_f32_32x32x16_bf16 v[170:185], v[158:161], v[250:253], v[170:185]
	v_mfma_f32_32x32x16_bf16 v[186:201], v[158:161], v[128:131], v[186:201]
	ds_read_b128 v[158:161], v122
	v_mfma_f32_32x32x16_bf16 v[16:31], v[162:165], v[166:169], v[16:31]
	ds_read_b128 v[166:169], v125 offset:8192
	v_mfma_f32_32x32x16_bf16 v[0:15], v[162:165], v[244:247], v[0:15]
	ds_read_b128 v[244:247], v125 offset:10240
	v_mfma_f32_32x32x16_bf16 v[202:217], v[162:165], v[250:253], v[202:217]
	ds_read_b128 v[250:253], v125 offset:49152
	v_mfma_f32_32x32x16_bf16 v[226:241], v[162:165], v[128:131], v[226:241]
	ds_read_b128 v[162:165], v122 offset:2048
	ds_read_b128 v[128:131], v125 offset:51200
	s_waitcnt lgkmcnt(6)
	v_mfma_f32_32x32x16_bf16 v[32:47], v[134:137], v[142:145], v[32:47]
	s_mov_b32 m0, s52
	v_lshl_add_u64 v[96:97], v[96:97], 0, s[44:45]
	global_load_lds_dwordx4 v[96:97], off
	v_mfma_f32_32x32x16_bf16 v[48:63], v[134:137], v[146:149], v[48:63]
	global_load_lds_dwordx4 v[96:97], off offset:1024
	v_mfma_f32_32x32x16_bf16 v[170:185], v[134:137], v[150:153], v[170:185]
	s_mov_b32 m0, s55
	v_lshl_add_u64 v[98:99], v[98:99], 0, s[44:45]
	global_load_lds_dwordx4 v[98:99], off
	v_mfma_f32_32x32x16_bf16 v[186:201], v[134:137], v[154:157], v[186:201]
	global_load_lds_dwordx4 v[98:99], off offset:1024
	v_mfma_f32_32x32x16_bf16 v[16:31], v[138:141], v[142:145], v[16:31]
	s_mov_b32 m0, s58
	v_lshl_add_u64 v[114:115], v[98:99], 0, s[72:73]
	global_load_lds_dwordx4 v[114:115], off
	v_mfma_f32_32x32x16_bf16 v[0:15], v[138:141], v[146:149], v[0:15]
	global_load_lds_dwordx4 v[114:115], off offset:1024
	v_mfma_f32_32x32x16_bf16 v[202:217], v[138:141], v[150:153], v[202:217]
	v_mfma_f32_32x32x16_bf16 v[226:241], v[138:141], v[154:157], v[226:241]
	s_waitcnt vmcnt(6)
	s_waitcnt lgkmcnt(0)
	s_barrier
	ds_read_b128 v[134:137], v113 offset:16384
	ds_read_b128 v[142:145], v119 offset:24576
	v_mfma_f32_32x32x16_bf16 v[32:47], v[158:161], v[166:169], v[32:47]
	ds_read_b128 v[146:149], v119 offset:26624
	ds_read_b128 v[150:153], v132 offset:40960
	v_mfma_f32_32x32x16_bf16 v[48:63], v[158:161], v[244:247], v[48:63]
	ds_read_b128 v[154:157], v132 offset:43008
	ds_read_b128 v[138:141], v113 offset:18432
	v_mfma_f32_32x32x16_bf16 v[170:185], v[158:161], v[250:253], v[170:185]
	v_mfma_f32_32x32x16_bf16 v[186:201], v[158:161], v[128:131], v[186:201]
	ds_read_b128 v[158:161], v122 offset:16384
	v_mfma_f32_32x32x16_bf16 v[16:31], v[162:165], v[166:169], v[16:31]
	ds_read_b128 v[166:169], v125 offset:24576
	v_mfma_f32_32x32x16_bf16 v[0:15], v[162:165], v[244:247], v[0:15]
	ds_read_b128 v[244:247], v125 offset:26624
	v_mfma_f32_32x32x16_bf16 v[202:217], v[162:165], v[250:253], v[202:217]
	ds_read_b128 v[250:253], v133 offset:40960
	v_mfma_f32_32x32x16_bf16 v[226:241], v[162:165], v[128:131], v[226:241]
	ds_read_b128 v[162:165], v122 offset:18432
	ds_read_b128 v[128:131], v133 offset:43008
	s_waitcnt lgkmcnt(6)
	v_mfma_f32_32x32x16_bf16 v[32:47], v[134:137], v[142:145], v[32:47]
	s_mov_b32 m0, s50
	v_lshl_add_u64 v[96:97], v[96:97], 0, s[44:45]
	global_load_lds_dwordx4 v[96:97], off
	v_mfma_f32_32x32x16_bf16 v[48:63], v[134:137], v[146:149], v[48:63]
	global_load_lds_dwordx4 v[96:97], off offset:1024
	v_mfma_f32_32x32x16_bf16 v[170:185], v[134:137], v[150:153], v[170:185]
	s_mov_b32 m0, s53
	v_lshl_add_u64 v[98:99], v[98:99], 0, s[44:45]
	global_load_lds_dwordx4 v[98:99], off
	v_mfma_f32_32x32x16_bf16 v[186:201], v[134:137], v[154:157], v[186:201]
	global_load_lds_dwordx4 v[98:99], off offset:1024
	v_mfma_f32_32x32x16_bf16 v[16:31], v[138:141], v[142:145], v[16:31]
	s_mov_b32 m0, s56
	v_lshl_add_u64 v[114:115], v[98:99], 0, s[72:73]
	global_load_lds_dwordx4 v[114:115], off
	v_mfma_f32_32x32x16_bf16 v[0:15], v[138:141], v[146:149], v[0:15]
	global_load_lds_dwordx4 v[114:115], off offset:1024
	v_mfma_f32_32x32x16_bf16 v[202:217], v[138:141], v[150:153], v[202:217]
	v_mfma_f32_32x32x16_bf16 v[226:241], v[138:141], v[154:157], v[226:241]
	s_waitcnt vmcnt(6)
	s_waitcnt lgkmcnt(0)
	s_barrier
	ds_read_b128 v[134:137], v113 offset:32768
	ds_read_b128 v[142:145], v119 offset:40960
	v_mfma_f32_32x32x16_bf16 v[32:47], v[158:161], v[166:169], v[32:47]
	ds_read_b128 v[146:149], v119 offset:43008
	ds_read_b128 v[150:153], v132 offset:57344
	v_mfma_f32_32x32x16_bf16 v[48:63], v[158:161], v[244:247], v[48:63]
	ds_read_b128 v[154:157], v132 offset:59392
	ds_read_b128 v[138:141], v113 offset:34816
	v_mfma_f32_32x32x16_bf16 v[170:185], v[158:161], v[250:253], v[170:185]
	v_mfma_f32_32x32x16_bf16 v[186:201], v[158:161], v[128:131], v[186:201]
	ds_read_b128 v[158:161], v122 offset:32768
	v_mfma_f32_32x32x16_bf16 v[16:31], v[162:165], v[166:169], v[16:31]
	ds_read_b128 v[166:169], v125 offset:40960
	v_mfma_f32_32x32x16_bf16 v[0:15], v[162:165], v[244:247], v[0:15]
	ds_read_b128 v[244:247], v125 offset:43008
	v_mfma_f32_32x32x16_bf16 v[202:217], v[162:165], v[250:253], v[202:217]
	ds_read_b128 v[250:253], v133 offset:57344
	v_mfma_f32_32x32x16_bf16 v[226:241], v[162:165], v[128:131], v[226:241]
	ds_read_b128 v[162:165], v122 offset:34816
	ds_read_b128 v[128:131], v133 offset:59392
	s_waitcnt lgkmcnt(6)
	v_mfma_f32_32x32x16_bf16 v[32:47], v[134:137], v[142:145], v[32:47]
	s_mov_b32 m0, s51
	v_lshl_add_u64 v[96:97], v[96:97], 0, s[44:45]
	global_load_lds_dwordx4 v[96:97], off
	v_mfma_f32_32x32x16_bf16 v[48:63], v[134:137], v[146:149], v[48:63]
	global_load_lds_dwordx4 v[96:97], off offset:1024
	v_mfma_f32_32x32x16_bf16 v[170:185], v[134:137], v[150:153], v[170:185]
	s_mov_b32 m0, s54
	v_lshl_add_u64 v[98:99], v[98:99], 0, s[44:45]
	global_load_lds_dwordx4 v[98:99], off
	v_mfma_f32_32x32x16_bf16 v[186:201], v[134:137], v[154:157], v[186:201]
	global_load_lds_dwordx4 v[98:99], off offset:1024
	v_mfma_f32_32x32x16_bf16 v[16:31], v[138:141], v[142:145], v[16:31]
	s_mov_b32 m0, s57
	v_lshl_add_u64 v[114:115], v[98:99], 0, s[72:73]
	global_load_lds_dwordx4 v[114:115], off
	v_mfma_f32_32x32x16_bf16 v[0:15], v[138:141], v[146:149], v[0:15]
	global_load_lds_dwordx4 v[114:115], off offset:1024
	v_mfma_f32_32x32x16_bf16 v[202:217], v[138:141], v[150:153], v[202:217]
	v_mfma_f32_32x32x16_bf16 v[226:241], v[138:141], v[154:157], v[226:241]
	s_waitcnt vmcnt(6)
	s_waitcnt lgkmcnt(0)
	s_barrier
	ds_read_b128 v[134:137], v113
	ds_read_b128 v[142:145], v119 offset:8192
	v_mfma_f32_32x32x16_bf16 v[32:47], v[158:161], v[166:169], v[32:47]
	ds_read_b128 v[146:149], v119 offset:10240
	ds_read_b128 v[150:153], v119 offset:49152
	v_mfma_f32_32x32x16_bf16 v[48:63], v[158:161], v[244:247], v[48:63]
	ds_read_b128 v[154:157], v119 offset:51200
	ds_read_b128 v[138:141], v113 offset:2048
	v_mfma_f32_32x32x16_bf16 v[170:185], v[158:161], v[250:253], v[170:185]
	v_mfma_f32_32x32x16_bf16 v[186:201], v[158:161], v[128:131], v[186:201]
	ds_read_b128 v[158:161], v122
	v_mfma_f32_32x32x16_bf16 v[16:31], v[162:165], v[166:169], v[16:31]
	ds_read_b128 v[166:169], v125 offset:8192
	v_mfma_f32_32x32x16_bf16 v[0:15], v[162:165], v[244:247], v[0:15]
	ds_read_b128 v[244:247], v125 offset:10240
	v_mfma_f32_32x32x16_bf16 v[202:217], v[162:165], v[250:253], v[202:217]
	ds_read_b128 v[250:253], v125 offset:49152
	v_mfma_f32_32x32x16_bf16 v[226:241], v[162:165], v[128:131], v[226:241]
	ds_read_b128 v[162:165], v122 offset:2048
	ds_read_b128 v[128:131], v125 offset:51200
	s_waitcnt lgkmcnt(6)
	v_mfma_f32_32x32x16_bf16 v[32:47], v[134:137], v[142:145], v[32:47]
	s_mov_b32 m0, s52
	v_lshl_add_u64 v[96:97], v[96:97], 0, s[44:45]
	global_load_lds_dwordx4 v[96:97], off
	v_mfma_f32_32x32x16_bf16 v[48:63], v[134:137], v[146:149], v[48:63]
	global_load_lds_dwordx4 v[96:97], off offset:1024
	v_mfma_f32_32x32x16_bf16 v[170:185], v[134:137], v[150:153], v[170:185]
	s_mov_b32 m0, s55
	v_lshl_add_u64 v[98:99], v[98:99], 0, s[44:45]
	global_load_lds_dwordx4 v[98:99], off
	v_mfma_f32_32x32x16_bf16 v[186:201], v[134:137], v[154:157], v[186:201]
	global_load_lds_dwordx4 v[98:99], off offset:1024
	v_mfma_f32_32x32x16_bf16 v[16:31], v[138:141], v[142:145], v[16:31]
	s_mov_b32 m0, s58
	v_lshl_add_u64 v[114:115], v[98:99], 0, s[72:73]
	global_load_lds_dwordx4 v[114:115], off
	v_mfma_f32_32x32x16_bf16 v[0:15], v[138:141], v[146:149], v[0:15]
	global_load_lds_dwordx4 v[114:115], off offset:1024
	v_mfma_f32_32x32x16_bf16 v[202:217], v[138:141], v[150:153], v[202:217]
	v_mfma_f32_32x32x16_bf16 v[226:241], v[138:141], v[154:157], v[226:241]
	s_waitcnt vmcnt(6)
	s_waitcnt lgkmcnt(0)
	s_barrier
	ds_read_b128 v[134:137], v113 offset:16384
	ds_read_b128 v[142:145], v119 offset:24576
	v_mfma_f32_32x32x16_bf16 v[32:47], v[158:161], v[166:169], v[32:47]
	ds_read_b128 v[146:149], v119 offset:26624
	ds_read_b128 v[150:153], v132 offset:40960
	v_mfma_f32_32x32x16_bf16 v[48:63], v[158:161], v[244:247], v[48:63]
	ds_read_b128 v[154:157], v132 offset:43008
	ds_read_b128 v[138:141], v113 offset:18432
	v_mfma_f32_32x32x16_bf16 v[170:185], v[158:161], v[250:253], v[170:185]
	v_mfma_f32_32x32x16_bf16 v[186:201], v[158:161], v[128:131], v[186:201]
	ds_read_b128 v[158:161], v122 offset:16384
	v_mfma_f32_32x32x16_bf16 v[16:31], v[162:165], v[166:169], v[16:31]
	ds_read_b128 v[166:169], v125 offset:24576
	v_mfma_f32_32x32x16_bf16 v[0:15], v[162:165], v[244:247], v[0:15]
	ds_read_b128 v[244:247], v125 offset:26624
	v_mfma_f32_32x32x16_bf16 v[202:217], v[162:165], v[250:253], v[202:217]
	ds_read_b128 v[250:253], v133 offset:40960
	v_mfma_f32_32x32x16_bf16 v[226:241], v[162:165], v[128:131], v[226:241]
	ds_read_b128 v[162:165], v122 offset:18432
	ds_read_b128 v[128:131], v133 offset:43008
	s_waitcnt lgkmcnt(6)
	v_mfma_f32_32x32x16_bf16 v[32:47], v[134:137], v[142:145], v[32:47]
	s_mov_b32 m0, s50
	v_lshl_add_u64 v[96:97], v[96:97], 0, s[44:45]
	global_load_lds_dwordx4 v[96:97], off
	v_mfma_f32_32x32x16_bf16 v[48:63], v[134:137], v[146:149], v[48:63]
	global_load_lds_dwordx4 v[96:97], off offset:1024
	v_mfma_f32_32x32x16_bf16 v[170:185], v[134:137], v[150:153], v[170:185]
	s_mov_b32 m0, s53
	v_lshl_add_u64 v[98:99], v[98:99], 0, s[44:45]
	global_load_lds_dwordx4 v[98:99], off
	v_mfma_f32_32x32x16_bf16 v[186:201], v[134:137], v[154:157], v[186:201]
	global_load_lds_dwordx4 v[98:99], off offset:1024
	v_mfma_f32_32x32x16_bf16 v[16:31], v[138:141], v[142:145], v[16:31]
	s_mov_b32 m0, s56
	v_lshl_add_u64 v[114:115], v[98:99], 0, s[72:73]
	global_load_lds_dwordx4 v[114:115], off
	v_mfma_f32_32x32x16_bf16 v[0:15], v[138:141], v[146:149], v[0:15]
	global_load_lds_dwordx4 v[114:115], off offset:1024
	v_mfma_f32_32x32x16_bf16 v[202:217], v[138:141], v[150:153], v[202:217]
	v_mfma_f32_32x32x16_bf16 v[226:241], v[138:141], v[154:157], v[226:241]
	s_waitcnt vmcnt(6)
	s_waitcnt lgkmcnt(0)
	s_barrier
	ds_read_b128 v[134:137], v113 offset:32768
	ds_read_b128 v[142:145], v119 offset:40960
	v_mfma_f32_32x32x16_bf16 v[32:47], v[158:161], v[166:169], v[32:47]
	ds_read_b128 v[146:149], v119 offset:43008
	ds_read_b128 v[150:153], v132 offset:57344
	v_mfma_f32_32x32x16_bf16 v[48:63], v[158:161], v[244:247], v[48:63]
	ds_read_b128 v[154:157], v132 offset:59392
	ds_read_b128 v[138:141], v113 offset:34816
	v_mfma_f32_32x32x16_bf16 v[170:185], v[158:161], v[250:253], v[170:185]
	v_mfma_f32_32x32x16_bf16 v[186:201], v[158:161], v[128:131], v[186:201]
	ds_read_b128 v[158:161], v122 offset:32768
	v_mfma_f32_32x32x16_bf16 v[16:31], v[162:165], v[166:169], v[16:31]
	ds_read_b128 v[166:169], v125 offset:40960
	v_mfma_f32_32x32x16_bf16 v[0:15], v[162:165], v[244:247], v[0:15]
	ds_read_b128 v[244:247], v125 offset:43008
	v_mfma_f32_32x32x16_bf16 v[202:217], v[162:165], v[250:253], v[202:217]
	ds_read_b128 v[250:253], v133 offset:57344
	v_mfma_f32_32x32x16_bf16 v[226:241], v[162:165], v[128:131], v[226:241]
	ds_read_b128 v[162:165], v122 offset:34816
	ds_read_b128 v[128:131], v133 offset:59392
	s_waitcnt lgkmcnt(6)
	v_mfma_f32_32x32x16_bf16 v[32:47], v[134:137], v[142:145], v[32:47]
	s_mov_b32 m0, s51
	v_lshl_add_u64 v[96:97], v[96:97], 0, s[44:45]
	global_load_lds_dwordx4 v[96:97], off
	v_mfma_f32_32x32x16_bf16 v[48:63], v[134:137], v[146:149], v[48:63]
	global_load_lds_dwordx4 v[96:97], off offset:1024
	v_mfma_f32_32x32x16_bf16 v[170:185], v[134:137], v[150:153], v[170:185]
	s_mov_b32 m0, s54
	v_lshl_add_u64 v[98:99], v[98:99], 0, s[44:45]
	global_load_lds_dwordx4 v[98:99], off
	v_mfma_f32_32x32x16_bf16 v[186:201], v[134:137], v[154:157], v[186:201]
	global_load_lds_dwordx4 v[98:99], off offset:1024
	v_mfma_f32_32x32x16_bf16 v[16:31], v[138:141], v[142:145], v[16:31]
	s_mov_b32 m0, s57
	v_lshl_add_u64 v[114:115], v[98:99], 0, s[72:73]
	global_load_lds_dwordx4 v[114:115], off
	v_mfma_f32_32x32x16_bf16 v[0:15], v[138:141], v[146:149], v[0:15]
	global_load_lds_dwordx4 v[114:115], off offset:1024
	v_mfma_f32_32x32x16_bf16 v[202:217], v[138:141], v[150:153], v[202:217]
	v_mfma_f32_32x32x16_bf16 v[226:241], v[138:141], v[154:157], v[226:241]
	s_waitcnt vmcnt(6)
	s_waitcnt lgkmcnt(0)
	s_barrier
	ds_read_b128 v[134:137], v113
	ds_read_b128 v[142:145], v119 offset:8192
	v_mfma_f32_32x32x16_bf16 v[32:47], v[158:161], v[166:169], v[32:47]
	ds_read_b128 v[146:149], v119 offset:10240
	ds_read_b128 v[150:153], v119 offset:49152
	v_mfma_f32_32x32x16_bf16 v[48:63], v[158:161], v[244:247], v[48:63]
	ds_read_b128 v[154:157], v119 offset:51200
	ds_read_b128 v[138:141], v113 offset:2048
	v_mfma_f32_32x32x16_bf16 v[170:185], v[158:161], v[250:253], v[170:185]
	v_mfma_f32_32x32x16_bf16 v[186:201], v[158:161], v[128:131], v[186:201]
	ds_read_b128 v[158:161], v122
	v_mfma_f32_32x32x16_bf16 v[16:31], v[162:165], v[166:169], v[16:31]
	ds_read_b128 v[166:169], v125 offset:8192
	v_mfma_f32_32x32x16_bf16 v[0:15], v[162:165], v[244:247], v[0:15]
	ds_read_b128 v[244:247], v125 offset:10240
	v_mfma_f32_32x32x16_bf16 v[202:217], v[162:165], v[250:253], v[202:217]
	ds_read_b128 v[250:253], v125 offset:49152
	v_mfma_f32_32x32x16_bf16 v[226:241], v[162:165], v[128:131], v[226:241]
	ds_read_b128 v[162:165], v122 offset:2048
	ds_read_b128 v[128:131], v125 offset:51200
	s_waitcnt lgkmcnt(6)
	v_mfma_f32_32x32x16_bf16 v[32:47], v[134:137], v[142:145], v[32:47]
	s_mov_b32 m0, s52
	v_lshl_add_u64 v[96:97], v[96:97], 0, s[44:45]
	global_load_lds_dwordx4 v[96:97], off
	v_mfma_f32_32x32x16_bf16 v[48:63], v[134:137], v[146:149], v[48:63]
	global_load_lds_dwordx4 v[96:97], off offset:1024
	v_mfma_f32_32x32x16_bf16 v[170:185], v[134:137], v[150:153], v[170:185]
	s_mov_b32 m0, s55
	v_lshl_add_u64 v[98:99], v[98:99], 0, s[44:45]
	global_load_lds_dwordx4 v[98:99], off
	v_mfma_f32_32x32x16_bf16 v[186:201], v[134:137], v[154:157], v[186:201]
	global_load_lds_dwordx4 v[98:99], off offset:1024
	v_mfma_f32_32x32x16_bf16 v[16:31], v[138:141], v[142:145], v[16:31]
	s_mov_b32 m0, s58
	v_lshl_add_u64 v[114:115], v[98:99], 0, s[72:73]
	global_load_lds_dwordx4 v[114:115], off
	v_mfma_f32_32x32x16_bf16 v[0:15], v[138:141], v[146:149], v[0:15]
	global_load_lds_dwordx4 v[114:115], off offset:1024
	v_mfma_f32_32x32x16_bf16 v[202:217], v[138:141], v[150:153], v[202:217]
	v_mfma_f32_32x32x16_bf16 v[226:241], v[138:141], v[154:157], v[226:241]
	s_waitcnt vmcnt(6)
	s_waitcnt lgkmcnt(0)
	s_barrier
	ds_read_b128 v[134:137], v113 offset:16384
	ds_read_b128 v[142:145], v119 offset:24576
	v_mfma_f32_32x32x16_bf16 v[32:47], v[158:161], v[166:169], v[32:47]
	ds_read_b128 v[146:149], v119 offset:26624
	ds_read_b128 v[150:153], v132 offset:40960
	v_mfma_f32_32x32x16_bf16 v[48:63], v[158:161], v[244:247], v[48:63]
	ds_read_b128 v[154:157], v132 offset:43008
	ds_read_b128 v[138:141], v113 offset:18432
	v_mfma_f32_32x32x16_bf16 v[170:185], v[158:161], v[250:253], v[170:185]
	v_mfma_f32_32x32x16_bf16 v[186:201], v[158:161], v[128:131], v[186:201]
	ds_read_b128 v[158:161], v122 offset:16384
	v_mfma_f32_32x32x16_bf16 v[16:31], v[162:165], v[166:169], v[16:31]
	ds_read_b128 v[166:169], v125 offset:24576
	v_mfma_f32_32x32x16_bf16 v[0:15], v[162:165], v[244:247], v[0:15]
	ds_read_b128 v[244:247], v125 offset:26624
	v_mfma_f32_32x32x16_bf16 v[202:217], v[162:165], v[250:253], v[202:217]
	ds_read_b128 v[250:253], v133 offset:40960
	v_mfma_f32_32x32x16_bf16 v[226:241], v[162:165], v[128:131], v[226:241]
	ds_read_b128 v[162:165], v122 offset:18432
	ds_read_b128 v[128:131], v133 offset:43008
	s_waitcnt lgkmcnt(6)
	v_mfma_f32_32x32x16_bf16 v[32:47], v[134:137], v[142:145], v[32:47]
	s_mov_b32 m0, s50
	v_lshl_add_u64 v[96:97], v[96:97], 0, s[44:45]
	global_load_lds_dwordx4 v[96:97], off
	v_mfma_f32_32x32x16_bf16 v[48:63], v[134:137], v[146:149], v[48:63]
	global_load_lds_dwordx4 v[96:97], off offset:1024
	v_mfma_f32_32x32x16_bf16 v[170:185], v[134:137], v[150:153], v[170:185]
	s_mov_b32 m0, s53
	v_lshl_add_u64 v[98:99], v[98:99], 0, s[44:45]
	global_load_lds_dwordx4 v[98:99], off
	v_mfma_f32_32x32x16_bf16 v[186:201], v[134:137], v[154:157], v[186:201]
	global_load_lds_dwordx4 v[98:99], off offset:1024
	v_mfma_f32_32x32x16_bf16 v[16:31], v[138:141], v[142:145], v[16:31]
	s_mov_b32 m0, s56
	v_lshl_add_u64 v[114:115], v[98:99], 0, s[72:73]
	global_load_lds_dwordx4 v[114:115], off
	v_mfma_f32_32x32x16_bf16 v[0:15], v[138:141], v[146:149], v[0:15]
	global_load_lds_dwordx4 v[114:115], off offset:1024
	v_mfma_f32_32x32x16_bf16 v[202:217], v[138:141], v[150:153], v[202:217]
	v_mfma_f32_32x32x16_bf16 v[226:241], v[138:141], v[154:157], v[226:241]
	s_waitcnt vmcnt(6)
	s_waitcnt lgkmcnt(0)
	s_barrier
	ds_read_b128 v[134:137], v113 offset:32768
	ds_read_b128 v[142:145], v119 offset:40960
	v_mfma_f32_32x32x16_bf16 v[32:47], v[158:161], v[166:169], v[32:47]
	ds_read_b128 v[146:149], v119 offset:43008
	ds_read_b128 v[150:153], v132 offset:57344
	v_mfma_f32_32x32x16_bf16 v[48:63], v[158:161], v[244:247], v[48:63]
	ds_read_b128 v[154:157], v132 offset:59392
	ds_read_b128 v[138:141], v113 offset:34816
	v_mfma_f32_32x32x16_bf16 v[170:185], v[158:161], v[250:253], v[170:185]
	v_mfma_f32_32x32x16_bf16 v[186:201], v[158:161], v[128:131], v[186:201]
	ds_read_b128 v[158:161], v122 offset:32768
	v_mfma_f32_32x32x16_bf16 v[16:31], v[162:165], v[166:169], v[16:31]
	ds_read_b128 v[166:169], v125 offset:40960
	v_mfma_f32_32x32x16_bf16 v[0:15], v[162:165], v[244:247], v[0:15]
	ds_read_b128 v[244:247], v125 offset:43008
	v_mfma_f32_32x32x16_bf16 v[202:217], v[162:165], v[250:253], v[202:217]
	ds_read_b128 v[250:253], v133 offset:57344
	v_mfma_f32_32x32x16_bf16 v[226:241], v[162:165], v[128:131], v[226:241]
	ds_read_b128 v[162:165], v122 offset:34816
	ds_read_b128 v[128:131], v133 offset:59392
	s_waitcnt lgkmcnt(6)
	v_mfma_f32_32x32x16_bf16 v[32:47], v[134:137], v[142:145], v[32:47]
	s_mov_b32 m0, s51
	v_lshl_add_u64 v[96:97], v[96:97], 0, s[44:45]
	global_load_lds_dwordx4 v[96:97], off
	v_mfma_f32_32x32x16_bf16 v[48:63], v[134:137], v[146:149], v[48:63]
	global_load_lds_dwordx4 v[96:97], off offset:1024
	v_mfma_f32_32x32x16_bf16 v[170:185], v[134:137], v[150:153], v[170:185]
	s_mov_b32 m0, s54
	v_lshl_add_u64 v[98:99], v[98:99], 0, s[44:45]
	global_load_lds_dwordx4 v[98:99], off
	v_mfma_f32_32x32x16_bf16 v[186:201], v[134:137], v[154:157], v[186:201]
	global_load_lds_dwordx4 v[98:99], off offset:1024
	v_mfma_f32_32x32x16_bf16 v[16:31], v[138:141], v[142:145], v[16:31]
	s_mov_b32 m0, s57
	v_lshl_add_u64 v[114:115], v[98:99], 0, s[72:73]
	global_load_lds_dwordx4 v[114:115], off
	v_mfma_f32_32x32x16_bf16 v[0:15], v[138:141], v[146:149], v[0:15]
	global_load_lds_dwordx4 v[114:115], off offset:1024
	v_mfma_f32_32x32x16_bf16 v[202:217], v[138:141], v[150:153], v[202:217]
	v_mfma_f32_32x32x16_bf16 v[226:241], v[138:141], v[154:157], v[226:241]
	s_waitcnt vmcnt(6)
	s_waitcnt lgkmcnt(0)
	s_barrier
	ds_read_b128 v[134:137], v113
	ds_read_b128 v[142:145], v119 offset:8192
	v_mfma_f32_32x32x16_bf16 v[32:47], v[158:161], v[166:169], v[32:47]
	ds_read_b128 v[146:149], v119 offset:10240
	ds_read_b128 v[150:153], v119 offset:49152
	v_mfma_f32_32x32x16_bf16 v[48:63], v[158:161], v[244:247], v[48:63]
	ds_read_b128 v[154:157], v119 offset:51200
	ds_read_b128 v[138:141], v113 offset:2048
	v_mfma_f32_32x32x16_bf16 v[170:185], v[158:161], v[250:253], v[170:185]
	v_mfma_f32_32x32x16_bf16 v[186:201], v[158:161], v[128:131], v[186:201]
	ds_read_b128 v[158:161], v122
	v_mfma_f32_32x32x16_bf16 v[16:31], v[162:165], v[166:169], v[16:31]
	ds_read_b128 v[166:169], v125 offset:8192
	v_mfma_f32_32x32x16_bf16 v[0:15], v[162:165], v[244:247], v[0:15]
	ds_read_b128 v[244:247], v125 offset:10240
	v_mfma_f32_32x32x16_bf16 v[202:217], v[162:165], v[250:253], v[202:217]
	ds_read_b128 v[250:253], v125 offset:49152
	v_mfma_f32_32x32x16_bf16 v[226:241], v[162:165], v[128:131], v[226:241]
	ds_read_b128 v[162:165], v122 offset:2048
	ds_read_b128 v[128:131], v125 offset:51200
	s_waitcnt lgkmcnt(6)
	v_mfma_f32_32x32x16_bf16 v[32:47], v[134:137], v[142:145], v[32:47]
	s_mov_b32 m0, s52
	v_lshl_add_u64 v[96:97], v[96:97], 0, s[44:45]
	global_load_lds_dwordx4 v[96:97], off
	v_mfma_f32_32x32x16_bf16 v[48:63], v[134:137], v[146:149], v[48:63]
	global_load_lds_dwordx4 v[96:97], off offset:1024
	v_mfma_f32_32x32x16_bf16 v[170:185], v[134:137], v[150:153], v[170:185]
	s_mov_b32 m0, s55
	v_lshl_add_u64 v[98:99], v[98:99], 0, s[44:45]
	global_load_lds_dwordx4 v[98:99], off
	v_mfma_f32_32x32x16_bf16 v[186:201], v[134:137], v[154:157], v[186:201]
	global_load_lds_dwordx4 v[98:99], off offset:1024
	v_mfma_f32_32x32x16_bf16 v[16:31], v[138:141], v[142:145], v[16:31]
	s_mov_b32 m0, s58
	v_lshl_add_u64 v[114:115], v[98:99], 0, s[72:73]
	global_load_lds_dwordx4 v[114:115], off
	v_mfma_f32_32x32x16_bf16 v[0:15], v[138:141], v[146:149], v[0:15]
	global_load_lds_dwordx4 v[114:115], off offset:1024
	v_mfma_f32_32x32x16_bf16 v[202:217], v[138:141], v[150:153], v[202:217]
	v_mfma_f32_32x32x16_bf16 v[226:241], v[138:141], v[154:157], v[226:241]
	s_waitcnt vmcnt(6)
	s_waitcnt lgkmcnt(0)
	s_barrier
	ds_read_b128 v[134:137], v113 offset:16384
	ds_read_b128 v[142:145], v119 offset:24576
	v_mfma_f32_32x32x16_bf16 v[32:47], v[158:161], v[166:169], v[32:47]
	ds_read_b128 v[146:149], v119 offset:26624
	ds_read_b128 v[150:153], v132 offset:40960
	v_mfma_f32_32x32x16_bf16 v[48:63], v[158:161], v[244:247], v[48:63]
	ds_read_b128 v[154:157], v132 offset:43008
	ds_read_b128 v[138:141], v113 offset:18432
	v_mfma_f32_32x32x16_bf16 v[170:185], v[158:161], v[250:253], v[170:185]
	v_mfma_f32_32x32x16_bf16 v[186:201], v[158:161], v[128:131], v[186:201]
	ds_read_b128 v[158:161], v122 offset:16384
	v_mfma_f32_32x32x16_bf16 v[16:31], v[162:165], v[166:169], v[16:31]
	ds_read_b128 v[166:169], v125 offset:24576
	v_mfma_f32_32x32x16_bf16 v[0:15], v[162:165], v[244:247], v[0:15]
	ds_read_b128 v[244:247], v125 offset:26624
	v_mfma_f32_32x32x16_bf16 v[202:217], v[162:165], v[250:253], v[202:217]
	ds_read_b128 v[250:253], v133 offset:40960
	v_mfma_f32_32x32x16_bf16 v[226:241], v[162:165], v[128:131], v[226:241]
	ds_read_b128 v[162:165], v122 offset:18432
	ds_read_b128 v[128:131], v133 offset:43008
	s_waitcnt lgkmcnt(6)
	v_mfma_f32_32x32x16_bf16 v[32:47], v[134:137], v[142:145], v[32:47]
	s_mov_b32 m0, s50
	v_lshl_add_u64 v[96:97], v[96:97], 0, s[44:45]
	global_load_lds_dwordx4 v[96:97], off
	v_mfma_f32_32x32x16_bf16 v[48:63], v[134:137], v[146:149], v[48:63]
	global_load_lds_dwordx4 v[96:97], off offset:1024
	v_mfma_f32_32x32x16_bf16 v[170:185], v[134:137], v[150:153], v[170:185]
	s_mov_b32 m0, s53
	v_lshl_add_u64 v[98:99], v[98:99], 0, s[44:45]
	global_load_lds_dwordx4 v[98:99], off
	v_mfma_f32_32x32x16_bf16 v[186:201], v[134:137], v[154:157], v[186:201]
	global_load_lds_dwordx4 v[98:99], off offset:1024
	v_mfma_f32_32x32x16_bf16 v[16:31], v[138:141], v[142:145], v[16:31]
	s_mov_b32 m0, s56
	v_lshl_add_u64 v[114:115], v[98:99], 0, s[72:73]
	global_load_lds_dwordx4 v[114:115], off
	v_mfma_f32_32x32x16_bf16 v[0:15], v[138:141], v[146:149], v[0:15]
	global_load_lds_dwordx4 v[114:115], off offset:1024
	v_mfma_f32_32x32x16_bf16 v[202:217], v[138:141], v[150:153], v[202:217]
	v_mfma_f32_32x32x16_bf16 v[226:241], v[138:141], v[154:157], v[226:241]
	s_waitcnt vmcnt(6)
	s_waitcnt lgkmcnt(0)
	s_barrier
	ds_read_b128 v[134:137], v113 offset:32768
	ds_read_b128 v[142:145], v119 offset:40960
	v_mfma_f32_32x32x16_bf16 v[32:47], v[158:161], v[166:169], v[32:47]
	ds_read_b128 v[146:149], v119 offset:43008
	ds_read_b128 v[150:153], v132 offset:57344
	v_mfma_f32_32x32x16_bf16 v[48:63], v[158:161], v[244:247], v[48:63]
	ds_read_b128 v[154:157], v132 offset:59392
	ds_read_b128 v[138:141], v113 offset:34816
	v_mfma_f32_32x32x16_bf16 v[170:185], v[158:161], v[250:253], v[170:185]
	v_mfma_f32_32x32x16_bf16 v[186:201], v[158:161], v[128:131], v[186:201]
	ds_read_b128 v[158:161], v122 offset:32768
	v_mfma_f32_32x32x16_bf16 v[16:31], v[162:165], v[166:169], v[16:31]
	ds_read_b128 v[166:169], v125 offset:40960
	v_mfma_f32_32x32x16_bf16 v[0:15], v[162:165], v[244:247], v[0:15]
	ds_read_b128 v[244:247], v125 offset:43008
	v_mfma_f32_32x32x16_bf16 v[202:217], v[162:165], v[250:253], v[202:217]
	ds_read_b128 v[250:253], v133 offset:57344
	v_mfma_f32_32x32x16_bf16 v[226:241], v[162:165], v[128:131], v[226:241]
	ds_read_b128 v[162:165], v122 offset:34816
	ds_read_b128 v[128:131], v133 offset:59392
	s_waitcnt lgkmcnt(6)
	v_mfma_f32_32x32x16_bf16 v[32:47], v[134:137], v[142:145], v[32:47]
	s_mov_b32 m0, s51
	v_lshl_add_u64 v[96:97], v[96:97], 0, s[44:45]
	global_load_lds_dwordx4 v[96:97], off
	v_mfma_f32_32x32x16_bf16 v[48:63], v[134:137], v[146:149], v[48:63]
	global_load_lds_dwordx4 v[96:97], off offset:1024
	v_mfma_f32_32x32x16_bf16 v[170:185], v[134:137], v[150:153], v[170:185]
	s_mov_b32 m0, s54
	v_lshl_add_u64 v[98:99], v[98:99], 0, s[44:45]
	global_load_lds_dwordx4 v[98:99], off
	v_mfma_f32_32x32x16_bf16 v[186:201], v[134:137], v[154:157], v[186:201]
	global_load_lds_dwordx4 v[98:99], off offset:1024
	v_mfma_f32_32x32x16_bf16 v[16:31], v[138:141], v[142:145], v[16:31]
	s_mov_b32 m0, s57
	v_lshl_add_u64 v[114:115], v[98:99], 0, s[72:73]
	global_load_lds_dwordx4 v[114:115], off
	v_mfma_f32_32x32x16_bf16 v[0:15], v[138:141], v[146:149], v[0:15]
	global_load_lds_dwordx4 v[114:115], off offset:1024
	v_mfma_f32_32x32x16_bf16 v[202:217], v[138:141], v[150:153], v[202:217]
	v_mfma_f32_32x32x16_bf16 v[226:241], v[138:141], v[154:157], v[226:241]
	s_waitcnt vmcnt(6)
	s_waitcnt lgkmcnt(0)
	s_barrier
	ds_read_b128 v[134:137], v113
	ds_read_b128 v[142:145], v119 offset:8192
	v_mfma_f32_32x32x16_bf16 v[32:47], v[158:161], v[166:169], v[32:47]
	ds_read_b128 v[146:149], v119 offset:10240
	ds_read_b128 v[150:153], v119 offset:49152
	v_mfma_f32_32x32x16_bf16 v[48:63], v[158:161], v[244:247], v[48:63]
	ds_read_b128 v[154:157], v119 offset:51200
	ds_read_b128 v[138:141], v113 offset:2048
	v_mfma_f32_32x32x16_bf16 v[170:185], v[158:161], v[250:253], v[170:185]
	v_mfma_f32_32x32x16_bf16 v[186:201], v[158:161], v[128:131], v[186:201]
	ds_read_b128 v[158:161], v122
	v_mfma_f32_32x32x16_bf16 v[16:31], v[162:165], v[166:169], v[16:31]
	ds_read_b128 v[166:169], v125 offset:8192
	v_mfma_f32_32x32x16_bf16 v[0:15], v[162:165], v[244:247], v[0:15]
	ds_read_b128 v[244:247], v125 offset:10240
	v_mfma_f32_32x32x16_bf16 v[202:217], v[162:165], v[250:253], v[202:217]
	ds_read_b128 v[250:253], v125 offset:49152
	v_mfma_f32_32x32x16_bf16 v[226:241], v[162:165], v[128:131], v[226:241]
	ds_read_b128 v[162:165], v122 offset:2048
	ds_read_b128 v[128:131], v125 offset:51200
	s_waitcnt lgkmcnt(6)
	v_mfma_f32_32x32x16_bf16 v[32:47], v[134:137], v[142:145], v[32:47]
	s_mov_b32 m0, s52
	v_lshl_add_u64 v[96:97], v[96:97], 0, s[44:45]
	global_load_lds_dwordx4 v[96:97], off
	v_mfma_f32_32x32x16_bf16 v[48:63], v[134:137], v[146:149], v[48:63]
	global_load_lds_dwordx4 v[96:97], off offset:1024
	v_mfma_f32_32x32x16_bf16 v[170:185], v[134:137], v[150:153], v[170:185]
	s_mov_b32 m0, s55
	v_lshl_add_u64 v[98:99], v[98:99], 0, s[44:45]
	global_load_lds_dwordx4 v[98:99], off
	v_mfma_f32_32x32x16_bf16 v[186:201], v[134:137], v[154:157], v[186:201]
	global_load_lds_dwordx4 v[98:99], off offset:1024
	v_mfma_f32_32x32x16_bf16 v[16:31], v[138:141], v[142:145], v[16:31]
	s_mov_b32 m0, s58
	v_lshl_add_u64 v[114:115], v[98:99], 0, s[72:73]
	global_load_lds_dwordx4 v[114:115], off
	v_mfma_f32_32x32x16_bf16 v[0:15], v[138:141], v[146:149], v[0:15]
	global_load_lds_dwordx4 v[114:115], off offset:1024
	v_mfma_f32_32x32x16_bf16 v[202:217], v[138:141], v[150:153], v[202:217]
	v_mfma_f32_32x32x16_bf16 v[226:241], v[138:141], v[154:157], v[226:241]
	s_waitcnt vmcnt(6)
	s_waitcnt lgkmcnt(0)
	s_barrier
	ds_read_b128 v[134:137], v113 offset:16384
	ds_read_b128 v[142:145], v119 offset:24576
	v_mfma_f32_32x32x16_bf16 v[32:47], v[158:161], v[166:169], v[32:47]
	ds_read_b128 v[146:149], v119 offset:26624
	ds_read_b128 v[150:153], v132 offset:40960
	v_mfma_f32_32x32x16_bf16 v[48:63], v[158:161], v[244:247], v[48:63]
	ds_read_b128 v[154:157], v132 offset:43008
	ds_read_b128 v[138:141], v113 offset:18432
	v_mfma_f32_32x32x16_bf16 v[170:185], v[158:161], v[250:253], v[170:185]
	v_mfma_f32_32x32x16_bf16 v[186:201], v[158:161], v[128:131], v[186:201]
	ds_read_b128 v[158:161], v122 offset:16384
	v_mfma_f32_32x32x16_bf16 v[16:31], v[162:165], v[166:169], v[16:31]
	ds_read_b128 v[166:169], v125 offset:24576
	v_mfma_f32_32x32x16_bf16 v[0:15], v[162:165], v[244:247], v[0:15]
	ds_read_b128 v[244:247], v125 offset:26624
	v_mfma_f32_32x32x16_bf16 v[202:217], v[162:165], v[250:253], v[202:217]
	ds_read_b128 v[250:253], v133 offset:40960
	v_mfma_f32_32x32x16_bf16 v[226:241], v[162:165], v[128:131], v[226:241]
	ds_read_b128 v[162:165], v122 offset:18432
	ds_read_b128 v[128:131], v133 offset:43008
	s_waitcnt lgkmcnt(6)
	v_mfma_f32_32x32x16_bf16 v[32:47], v[134:137], v[142:145], v[32:47]
	s_mov_b32 m0, s50
	v_lshl_add_u64 v[96:97], v[96:97], 0, s[44:45]
	global_load_lds_dwordx4 v[96:97], off
	v_mfma_f32_32x32x16_bf16 v[48:63], v[134:137], v[146:149], v[48:63]
	global_load_lds_dwordx4 v[96:97], off offset:1024
	v_mfma_f32_32x32x16_bf16 v[170:185], v[134:137], v[150:153], v[170:185]
	s_mov_b32 m0, s53
	v_lshl_add_u64 v[98:99], v[98:99], 0, s[44:45]
	global_load_lds_dwordx4 v[98:99], off
	v_mfma_f32_32x32x16_bf16 v[186:201], v[134:137], v[154:157], v[186:201]
	global_load_lds_dwordx4 v[98:99], off offset:1024
	v_mfma_f32_32x32x16_bf16 v[16:31], v[138:141], v[142:145], v[16:31]
	s_mov_b32 m0, s56
	v_lshl_add_u64 v[114:115], v[98:99], 0, s[72:73]
	global_load_lds_dwordx4 v[114:115], off
	v_mfma_f32_32x32x16_bf16 v[0:15], v[138:141], v[146:149], v[0:15]
	global_load_lds_dwordx4 v[114:115], off offset:1024
	v_mfma_f32_32x32x16_bf16 v[202:217], v[138:141], v[150:153], v[202:217]
	v_mfma_f32_32x32x16_bf16 v[226:241], v[138:141], v[154:157], v[226:241]
	s_waitcnt vmcnt(6)
	s_waitcnt lgkmcnt(0)
	s_barrier
	ds_read_b128 v[134:137], v113 offset:32768
	ds_read_b128 v[142:145], v119 offset:40960
	v_mfma_f32_32x32x16_bf16 v[32:47], v[158:161], v[166:169], v[32:47]
	ds_read_b128 v[146:149], v119 offset:43008
	ds_read_b128 v[150:153], v132 offset:57344
	v_mfma_f32_32x32x16_bf16 v[48:63], v[158:161], v[244:247], v[48:63]
	ds_read_b128 v[154:157], v132 offset:59392
	ds_read_b128 v[138:141], v113 offset:34816
	v_mfma_f32_32x32x16_bf16 v[170:185], v[158:161], v[250:253], v[170:185]
	v_mfma_f32_32x32x16_bf16 v[186:201], v[158:161], v[128:131], v[186:201]
	ds_read_b128 v[158:161], v122 offset:32768
	v_mfma_f32_32x32x16_bf16 v[16:31], v[162:165], v[166:169], v[16:31]
	ds_read_b128 v[166:169], v125 offset:40960
	v_mfma_f32_32x32x16_bf16 v[0:15], v[162:165], v[244:247], v[0:15]
	ds_read_b128 v[244:247], v125 offset:43008
	v_mfma_f32_32x32x16_bf16 v[202:217], v[162:165], v[250:253], v[202:217]
	ds_read_b128 v[250:253], v133 offset:57344
	v_mfma_f32_32x32x16_bf16 v[226:241], v[162:165], v[128:131], v[226:241]
	ds_read_b128 v[162:165], v122 offset:34816
	ds_read_b128 v[128:131], v133 offset:59392
	s_waitcnt lgkmcnt(6)
	v_mfma_f32_32x32x16_bf16 v[32:47], v[134:137], v[142:145], v[32:47]
	s_mov_b32 m0, s51
	v_lshl_add_u64 v[96:97], v[96:97], 0, s[44:45]
	global_load_lds_dwordx4 v[96:97], off
	v_mfma_f32_32x32x16_bf16 v[48:63], v[134:137], v[146:149], v[48:63]
	global_load_lds_dwordx4 v[96:97], off offset:1024
	v_mfma_f32_32x32x16_bf16 v[170:185], v[134:137], v[150:153], v[170:185]
	s_mov_b32 m0, s54
	v_lshl_add_u64 v[98:99], v[98:99], 0, s[44:45]
	global_load_lds_dwordx4 v[98:99], off
	v_mfma_f32_32x32x16_bf16 v[186:201], v[134:137], v[154:157], v[186:201]
	global_load_lds_dwordx4 v[98:99], off offset:1024
	v_mfma_f32_32x32x16_bf16 v[16:31], v[138:141], v[142:145], v[16:31]
	s_mov_b32 m0, s57
	v_lshl_add_u64 v[114:115], v[98:99], 0, s[72:73]
	global_load_lds_dwordx4 v[114:115], off
	v_mfma_f32_32x32x16_bf16 v[0:15], v[138:141], v[146:149], v[0:15]
	global_load_lds_dwordx4 v[114:115], off offset:1024
	v_mfma_f32_32x32x16_bf16 v[202:217], v[138:141], v[150:153], v[202:217]
	v_mfma_f32_32x32x16_bf16 v[226:241], v[138:141], v[154:157], v[226:241]
	s_waitcnt vmcnt(6)
	s_waitcnt lgkmcnt(0)
	s_barrier
	ds_read_b128 v[134:137], v113
	ds_read_b128 v[142:145], v119 offset:8192
	v_mfma_f32_32x32x16_bf16 v[32:47], v[158:161], v[166:169], v[32:47]
	ds_read_b128 v[146:149], v119 offset:10240
	ds_read_b128 v[150:153], v119 offset:49152
	v_mfma_f32_32x32x16_bf16 v[48:63], v[158:161], v[244:247], v[48:63]
	ds_read_b128 v[154:157], v119 offset:51200
	ds_read_b128 v[138:141], v113 offset:2048
	v_mfma_f32_32x32x16_bf16 v[170:185], v[158:161], v[250:253], v[170:185]
	v_mfma_f32_32x32x16_bf16 v[186:201], v[158:161], v[128:131], v[186:201]
	ds_read_b128 v[158:161], v122
	v_mfma_f32_32x32x16_bf16 v[16:31], v[162:165], v[166:169], v[16:31]
	ds_read_b128 v[166:169], v125 offset:8192
	v_mfma_f32_32x32x16_bf16 v[0:15], v[162:165], v[244:247], v[0:15]
	ds_read_b128 v[244:247], v125 offset:10240
	v_mfma_f32_32x32x16_bf16 v[202:217], v[162:165], v[250:253], v[202:217]
	ds_read_b128 v[250:253], v125 offset:49152
	v_mfma_f32_32x32x16_bf16 v[226:241], v[162:165], v[128:131], v[226:241]
	ds_read_b128 v[162:165], v122 offset:2048
	ds_read_b128 v[128:131], v125 offset:51200
	s_waitcnt lgkmcnt(6)
	v_mfma_f32_32x32x16_bf16 v[32:47], v[134:137], v[142:145], v[32:47]
	v_mfma_f32_32x32x16_bf16 v[48:63], v[134:137], v[146:149], v[48:63]
	v_mfma_f32_32x32x16_bf16 v[170:185], v[134:137], v[150:153], v[170:185]
	v_mfma_f32_32x32x16_bf16 v[186:201], v[134:137], v[154:157], v[186:201]
	v_mfma_f32_32x32x16_bf16 v[16:31], v[138:141], v[142:145], v[16:31]
	v_mfma_f32_32x32x16_bf16 v[0:15], v[138:141], v[146:149], v[0:15]
	v_mfma_f32_32x32x16_bf16 v[202:217], v[138:141], v[150:153], v[202:217]
	v_mfma_f32_32x32x16_bf16 v[226:241], v[138:141], v[154:157], v[226:241]
	s_waitcnt vmcnt(0)
	s_waitcnt lgkmcnt(0)
	s_barrier
	ds_read_b128 v[134:137], v113 offset:16384
	ds_read_b128 v[142:145], v119 offset:24576
	v_mfma_f32_32x32x16_bf16 v[32:47], v[158:161], v[166:169], v[32:47]
	ds_read_b128 v[146:149], v119 offset:26624
	ds_read_b128 v[150:153], v132 offset:40960
	v_mfma_f32_32x32x16_bf16 v[48:63], v[158:161], v[244:247], v[48:63]
	ds_read_b128 v[154:157], v132 offset:43008
	ds_read_b128 v[138:141], v113 offset:18432
	v_mfma_f32_32x32x16_bf16 v[170:185], v[158:161], v[250:253], v[170:185]
	v_mfma_f32_32x32x16_bf16 v[186:201], v[158:161], v[128:131], v[186:201]
	ds_read_b128 v[158:161], v122 offset:16384
	v_mfma_f32_32x32x16_bf16 v[16:31], v[162:165], v[166:169], v[16:31]
	ds_read_b128 v[166:169], v125 offset:24576
	v_mfma_f32_32x32x16_bf16 v[0:15], v[162:165], v[244:247], v[0:15]
	ds_read_b128 v[244:247], v125 offset:26624
	v_mfma_f32_32x32x16_bf16 v[202:217], v[162:165], v[250:253], v[202:217]
	ds_read_b128 v[250:253], v133 offset:40960
	v_mfma_f32_32x32x16_bf16 v[226:241], v[162:165], v[128:131], v[226:241]
	ds_read_b128 v[162:165], v122 offset:18432
	ds_read_b128 v[128:131], v133 offset:43008
	s_waitcnt lgkmcnt(6)
	v_mfma_f32_32x32x16_bf16 v[32:47], v[134:137], v[142:145], v[32:47]
	v_mfma_f32_32x32x16_bf16 v[48:63], v[134:137], v[146:149], v[48:63]
	v_mfma_f32_32x32x16_bf16 v[170:185], v[134:137], v[150:153], v[170:185]
	v_mfma_f32_32x32x16_bf16 v[186:201], v[134:137], v[154:157], v[186:201]
	v_mfma_f32_32x32x16_bf16 v[16:31], v[138:141], v[142:145], v[16:31]
	v_mfma_f32_32x32x16_bf16 v[0:15], v[138:141], v[146:149], v[0:15]
	v_mfma_f32_32x32x16_bf16 v[202:217], v[138:141], v[150:153], v[202:217]
	v_mfma_f32_32x32x16_bf16 v[226:241], v[138:141], v[154:157], v[226:241]
	s_waitcnt lgkmcnt(0)
	v_mfma_f32_32x32x16_bf16 v[32:47], v[158:161], v[166:169], v[32:47]
	v_mfma_f32_32x32x16_bf16 v[48:63], v[158:161], v[244:247], v[48:63]
	v_mfma_f32_32x32x16_bf16 v[170:185], v[158:161], v[250:253], v[170:185]
	v_mfma_f32_32x32x16_bf16 v[186:201], v[158:161], v[128:131], v[186:201]
	v_mfma_f32_32x32x16_bf16 v[16:31], v[162:165], v[166:169], v[16:31]
	v_mfma_f32_32x32x16_bf16 v[0:15], v[162:165], v[244:247], v[0:15]
	v_mfma_f32_32x32x16_bf16 v[202:217], v[162:165], v[250:253], v[202:217]
	v_mfma_f32_32x32x16_bf16 v[226:241], v[162:165], v[128:131], v[226:241]
	v_add_u32_e32 v132, 0x400, v100
	v_add_u32_e32 v131, 0x2000, v100
	v_add_u32_e32 v130, 0x2400, v100
	v_add_u32_e32 v129, 0x4000, v100
	v_add_u32_e32 v128, 0x4400, v100
	v_add_u32_e32 v125, 0x6000, v100
	v_add_u32_e32 v122, 0x6400, v100
	v_add_u32_e32 v119, 0x8000, v100
	v_add_u32_e32 v115, 0x8400, v100
	v_add_u32_e32 v114, 0xa000, v100
	v_add_u32_e32 v113, 0xa400, v100
	s_branch .Lin_post

.Lin_post:
	s_and_saveexec_b64 s[16:17], s[36:37]
	s_cbranch_execz .LBB0_298
	s_mov_b32 s11, 0x800000
	v_mul_f32_e32 v96, 0x4b800000, v121
	v_cmp_gt_f32_e32 vcc, s11, v121
	s_nop 1
	v_cndmask_b32_e32 v96, v121, v96, vcc
	v_rsq_f32_e32 v96, v96
	s_nop 0
	v_mul_f32_e32 v97, 0x45800000, v96
	v_cndmask_b32_e32 v96, v96, v97, vcc
	ds_write_b32 v105, v96

.LBB0_300:
	s_cmp_eq_u32 s62, 1
	s_cbranch_scc0 .Lin_ein
	s_mov_b32 s60, s48
	s_mov_b32 s61, s43
	s_mov_b32 s48, s10
	s_add_i32 s43, s8, 0x80
	s_mov_b32 s62, 2

.LBB0_305:
	s_cmp_eq_u32 s13, 8
	s_cbranch_scc0 .Lin_orig2
	s_cmp_lt_u32 s20, 64
	s_cbranch_scc0 .Lid_s2
	s_mul_hi_u32 s43, s20, 0x2aaaaaab
	s_mul_i32 s9, s43, 6
	s_sub_i32 s9, s20, s9
	s_lshl_b32 s43, s43, 1
	s_branch .Lid_e2
.Lid_s2:
	s_add_i32 s9, s20, 0xffffffc0
	s_cmp_lt_u32 s9, 4
	s_cbranch_scc0 .Lid_t2
	s_and_b32 s43, s9, 1
	s_add_i32 s43, s43, 20
	s_lshr_b32 s9, s9, 1
	s_add_i32 s9, s9, 4
	s_branch .Lid_e2
.Lid_t2:
	s_add_i32 s9, s9, -4
	s_mul_hi_u32 s43, s9, 0x2aaaaaab
	s_mul_i32 s11, s43, 6
	s_sub_i32 s9, s9, s11
	s_add_i32 s43, s43, 22
.Lid_e2:
	s_lshl_b32 s48, s9, 3
	s_and_b32 s9, s74, 7
	s_or_b32 s48, s48, s9
	s_lshl_b32 s48, s48, 7
	s_lshl_b32 s43, s43, 7
	s_add_i32 s20, s20, 64
	s_mov_b64 s[14:15], -1
	s_mov_b64 s[0:1], -1
	s_branch .LBB0_290
